# merge GEMM K-loop: next-stage global loads issued right after the LDS writes into separate staging registers (v192-v223) with precomputed addresses
# speedup vs baseline: 1.0101x; 1.0034x over previous
;   __device__ __forceinline__ half_t* u() const { return (half_t*)(ws() + OFF_u); }
;   __device__ __forceinline__ half_t* wpT() const { return (half_t*)(ws() + OFF_wpT); }
;   __device__ __forceinline__ half_t* ya() const { return (half_t*)(ws() + OFF_ya); }
;   __device__ __forceinline__ half_t* yb() const { return (half_t*)(ws() + OFF_yb); }
;   __device__ __forceinline__ half_t* yc() const { return (half_t*)(ws() + OFF_yc); }
; template <int NI, class LA, class LB, class EP>
; __device__ __forceinline__ void gemm_tile(int K, LA loadA, LB loadB, EP epi, char* smem) {
;     ...
;   f32x16 acc[2][NI];
; #pragma unroll
;   for (int i = 0; i < 2; ++i)
; #pragma unroll
;     for (int j = 0; j < NI; ++j)
; #pragma unroll
;       for (int r = 0; r < 16; ++r) acc[i][j][r] = 0.f;
;   const int lr = tid >> 3, lc = (tid & 7) * 8;
;   uint4 ra[4], rb[NB];
; #pragma unroll
;   for (int i = 0; i < 4; ++i) ra[i] = loadA(lr + 32 * i, lc);
; #pragma unroll
;   for (int i = 0; i < NB; ++i) rb[i] = loadB(lr + 32 * i, lc);
; __device__ __forceinline__ void phase_merge(const KP& p, char* smem, int* q, int xcc) {
;     ...
;     for (int br = 0; br < 3; ++br) {
;       const half_t* A = (br == 0 ? p.ya() : (br == 1 ? p.yb() : p.yc())) + (size_t)m0 * 512;
;       const half_t* B = p.wpT() + (size_t)br * DM * 512 + (size_t)n0 * 512;
;       const half_t* G = p.u() + (size_t)m0 * NU + C_GM + br * 1024 + n0;
;       gemm_tile<2>(
.LBB0_1742:
	s_cmp_eq_u32 s56, 1
	s_mov_b32 s2, 0x174a0200
	s_cselect_b32 s2, s2, 0x184a0200
	s_cmp_lg_u32 s56, 0
	v_mov_b32_e32 v169, v224
	s_cselect_b32 s57, s2, 0x164a0200
	s_add_u32 s2, s15, s57
	v_lshlrev_b32_e32 v0, 3, v169
	v_ashrrev_i32_e32 v2, 3, v169
	v_and_b32_e32 v16, 56, v0
	s_addc_u32 s3, s49, 0
	v_lshlrev_b32_e32 v0, 1, v16
	v_ashrrev_i32_e32 v3, 31, v2
	v_lshl_add_u64 v[4:5], s[2:3], 0, v[0:1]
	v_lshlrev_b64 v[6:7], 10, v[2:3]
	s_mov_b64 s[2:3], 0x8000
	s_lshl_b32 s40, s56, 20
	v_lshl_add_u64 v[8:9], v[4:5], 0, v[6:7]
	v_lshl_add_u64 v[10:11], v[6:7], 0, s[2:3]
	s_mov_b64 s[2:3], 0x18000
	s_add_u32 s40, s50, s40
	v_lshl_add_u64 v[12:13], v[4:5], 0, v[10:11]
	global_load_dwordx4 v[192:195], v[8:9], off
	global_load_dwordx4 v[196:199], v[12:13], off
	v_lshl_add_u64 v[8:9], v[6:7], 0, s[20:21]
	v_lshl_add_u64 v[14:15], v[6:7], 0, s[2:3]
	s_addc_u32 s41, s51, 0
	v_lshl_add_u64 v[12:13], v[4:5], 0, v[8:9]
	v_lshl_add_u64 v[4:5], v[4:5], 0, v[14:15]
	global_load_dwordx4 v[200:203], v[12:13], off
	global_load_dwordx4 v[204:207], v[4:5], off
	v_lshl_add_u64 v[4:5], s[40:41], 0, v[0:1]
	v_lshl_add_u64 v[12:13], v[4:5], 0, v[6:7]
	v_lshl_add_u64 v[8:9], v[4:5], 0, v[8:9]
	v_lshl_add_u64 v[10:11], v[4:5], 0, v[10:11]
	global_load_dwordx4 v[208:211], v[12:13], off
	global_load_dwordx4 v[212:215], v[10:11], off
	v_lshl_add_u64 v[4:5], v[4:5], 0, v[14:15]
	global_load_dwordx4 v[216:219], v[8:9], off
	global_load_dwordx4 v[220:223], v[4:5], off
	v_ashrrev_i32_e32 v0, 1, v169
	v_and_b32_e32 v170, 0xffffffc0, v0
	v_lshrrev_b32_e32 v4, 1, v169
	v_and_or_b32 v3, v169, 31, v170
	v_and_b32_e32 v0, 0x5f, v169
	v_and_b32_e32 v4, 16, v4
	v_mul_lo_u32 v2, v2, s37
	v_mad_u64_u32 v[162:163], s[2:3], v3, s36, v[4:5]
	v_add_lshl_u32 v172, v2, v16, 1
	v_mul_u32_u24_e32 v2, 0x48, v0
	v_lshl_add_u32 v163, v2, 1, v4
	v_and_b32_e32 v2, 7, v169
	s_add_u32 s2, s54, s57
	v_lshl_or_b32 v6, v2, 4, v6
	s_addc_u32 s3, s55, 0
	v_add_u32_e32 v171, 0x1200, v163
	v_lshl_add_u64 v[164:165], s[38:39], 0, v[6:7]
	v_lshl_add_u64 v[166:167], s[2:3], 0, v[6:7]
	s_mov_b64 s[2:3], 0x80
	v_lshl_add_u64 v[228:229], v[166:167], 0, s[2:3]
	s_nop 0
	v_add_co_u32_e32 v230, vcc, s73, v228
	s_nop 1
	v_addc_co_u32_e32 v231, vcc, 0, v229, vcc
	v_add_co_u32_e32 v232, vcc, s72, v228
	s_nop 1
	v_addc_co_u32_e32 v233, vcc, 0, v229, vcc
	v_add_co_u32_e32 v234, vcc, s77, v228
	s_nop 1
	v_addc_co_u32_e32 v235, vcc, 0, v229, vcc
	s_mov_b64 s[2:3], 0x15680080
	v_lshl_add_u64 v[238:239], v[164:165], 0, s[2:3]
	s_mov_b64 s[2:3], 0x15688080
	v_lshl_add_u64 v[240:241], v[164:165], 0, s[2:3]
	s_mov_b64 s[2:3], 0x15690080
	v_lshl_add_u64 v[242:243], v[164:165], 0, s[2:3]
	s_mov_b64 s[2:3], 0x15698080
	v_lshl_add_u64 v[244:245], v[164:165], 0, s[2:3]
	s_mov_b64 s[2:3], 0x80
	s_mov_b64 s[40:41], 0
	v_mov_b32_e32 v2, 0
	v_mov_b32_e32 v3, v168
	v_mov_b32_e32 v4, v168
	v_mov_b32_e32 v5, v168
	v_mov_b32_e32 v6, v168
	v_mov_b32_e32 v7, v168
	v_mov_b32_e32 v8, v168
	v_mov_b32_e32 v9, v168
	v_mov_b32_e32 v10, v168
	v_mov_b32_e32 v11, v168
	v_mov_b32_e32 v12, v168
	v_mov_b32_e32 v13, v168
	v_mov_b32_e32 v14, v168
	v_mov_b32_e32 v15, v168
	v_mov_b32_e32 v16, v168
	v_mov_b32_e32 v17, v168
	v_mov_b32_e32 v18, 0
	v_mov_b32_e32 v19, v168
	v_mov_b32_e32 v20, v168
	v_mov_b32_e32 v21, v168
	v_mov_b32_e32 v22, v168
	v_mov_b32_e32 v23, v168
	v_mov_b32_e32 v24, v168
	v_mov_b32_e32 v25, v168
	v_mov_b32_e32 v26, v168
	v_mov_b32_e32 v27, v168
	v_mov_b32_e32 v28, v168
	v_mov_b32_e32 v29, v168
	v_mov_b32_e32 v30, v168
	v_mov_b32_e32 v31, v168
	v_mov_b32_e32 v32, v168
	v_mov_b32_e32 v33, v168
	v_mov_b32_e32 v34, 0
	v_mov_b32_e32 v35, v168
	v_mov_b32_e32 v36, v168
	v_mov_b32_e32 v37, v168
	v_mov_b32_e32 v38, v168
	v_mov_b32_e32 v39, v168
	v_mov_b32_e32 v40, v168
	v_mov_b32_e32 v41, v168
	v_mov_b32_e32 v42, v168
	v_mov_b32_e32 v43, v168
	v_mov_b32_e32 v44, v168
	v_mov_b32_e32 v45, v168
	v_mov_b32_e32 v46, v168
	v_mov_b32_e32 v47, v168
	v_mov_b32_e32 v48, v168
	v_mov_b32_e32 v49, v168
	v_mov_b32_e32 v50, 0
	v_mov_b32_e32 v51, v168
	v_mov_b32_e32 v52, v168
	v_mov_b32_e32 v53, v168
	v_mov_b32_e32 v54, v168
	v_mov_b32_e32 v55, v168
	v_mov_b32_e32 v56, v168
	v_mov_b32_e32 v57, v168
	v_mov_b32_e32 v58, v168
	v_mov_b32_e32 v59, v168
	v_mov_b32_e32 v60, v168
	v_mov_b32_e32 v61, v168
	v_mov_b32_e32 v62, v168
	v_mov_b32_e32 v63, v168
	v_mov_b32_e32 v64, v168
	v_mov_b32_e32 v65, v168
; template <int NI, class LA, class LB, class EP>
; __device__ __forceinline__ void gemm_tile(int K, LA loadA, LB loadB, EP epi, char* smem) {
;     ...
;   for (int kt = 0; kt < nk; ++kt) {
;     __syncthreads();
; #pragma unroll
;     for (int i = 0; i < 4; ++i) *(uint4*)&sA[(lr + 32 * i) * 72 + lc] = ra[i];
; #pragma unroll
;     for (int i = 0; i < NB; ++i) *(uint4*)&sB[(lr + 32 * i) * 72 + lc] = rb[i];
;     __syncthreads();
;     if (kt + 1 < nk) {
;       const int kk = (kt + 1) * 64 + lc;
; #pragma unroll
;       for (int i = 0; i < 4; ++i) ra[i] = loadA(lr + 32 * i, kk);
; #pragma unroll
;       for (int i = 0; i < NB; ++i) rb[i] = loadB(lr + 32 * i, kk);
;     }
; #pragma unroll
;     for (int s = 0; s < 4; ++s) {
;       h8 af[2], bf[NI];
; #pragma unroll
;       for (int mi = 0; mi < 2; ++mi)
;         af[mi] = *(const h8*)&sA[(wm * 64 + mi * 32 + (lane & 31)) * 72 + s * 16 + (lane >> 5) * 8];
; #pragma unroll
;       for (int ni = 0; ni < NI; ++ni)
;         bf[ni] = *(const h8*)&sB[(wn * (NI * 32) + ni * 32 + (lane & 31)) * 72 + s * 16 + (lane >> 5) * 8];
; #pragma unroll
;       for (int mi = 0; mi < 2; ++mi)
; #pragma unroll
;         for (int ni = 0; ni < NI; ++ni)
;           acc[mi][ni] = __builtin_amdgcn_mfma_f32_32x32x16_f16(af[mi], bf[ni], acc[mi][ni], 0, 0, 0);
;     }
.LBB0_1743:
	s_waitcnt vmcnt(63) expcnt(7) lgkmcnt(15)
	s_barrier
	s_waitcnt vmcnt(7)
	ds_write_b128 v172, v[192:195]
	s_waitcnt vmcnt(6)
	ds_write_b128 v172, v[196:199] offset:4608
	s_waitcnt vmcnt(5)
	ds_write_b128 v172, v[200:203] offset:9216
	s_waitcnt vmcnt(4)
	ds_write_b128 v172, v[204:207] offset:13824
	s_waitcnt vmcnt(3)
	ds_write_b128 v172, v[208:211] offset:18432
	s_waitcnt vmcnt(2)
	ds_write_b128 v172, v[212:215] offset:23040
	s_waitcnt vmcnt(1)
	ds_write_b128 v172, v[216:219] offset:27648
	s_waitcnt vmcnt(0)
	ds_write_b128 v172, v[220:223] offset:32256
	global_load_dwordx4 v[192:195], v[228:229], off
	global_load_dwordx4 v[196:199], v[230:231], off
	global_load_dwordx4 v[200:203], v[232:233], off
	global_load_dwordx4 v[204:207], v[234:235], off
	global_load_dwordx4 v[208:211], v[238:239], off
	global_load_dwordx4 v[212:215], v[240:241], off
	global_load_dwordx4 v[216:219], v[242:243], off
	global_load_dwordx4 v[220:223], v[244:245], off
	s_waitcnt lgkmcnt(0)
	s_barrier
	ds_read_b128 v[66:69], v162
	ds_read_b128 v[70:73], v163 offset:18432
	ds_read_b128 v[74:77], v162 offset:32
	ds_read_b128 v[78:81], v163 offset:18464
	ds_read_b128 v[82:85], v171 offset:18432
	ds_read_b128 v[174:177], v163 offset:23136
	s_waitcnt lgkmcnt(4)
	v_mfma_f32_32x32x16_f16 v[50:65], v[66:69], v[70:73], v[50:65]
	s_waitcnt lgkmcnt(1)
	v_mfma_f32_32x32x16_f16 v[34:49], v[66:69], v[82:85], v[34:49]
	v_lshl_add_u64 v[228:229], v[228:229], 0, s[2:3]
	ds_read_b128 v[66:69], v162 offset:4608
	ds_read_b128 v[86:89], v162 offset:4640
	s_waitcnt lgkmcnt(1)
	v_mfma_f32_32x32x16_f16 v[18:33], v[66:69], v[70:73], v[18:33]
	v_mfma_f32_32x32x16_f16 v[2:17], v[66:69], v[82:85], v[2:17]
	v_lshl_add_u64 v[230:231], v[230:231], 0, s[2:3]
	ds_read_b128 v[66:69], v163 offset:23072
	ds_read_b128 v[70:73], v163 offset:23104
	v_mfma_f32_32x32x16_f16 v[50:65], v[74:77], v[78:81], v[50:65]
	s_waitcnt lgkmcnt(1)
	v_mfma_f32_32x32x16_f16 v[34:49], v[74:77], v[66:69], v[34:49]
	v_lshl_add_u64 v[232:233], v[232:233], 0, s[2:3]
	v_mfma_f32_32x32x16_f16 v[18:33], v[86:89], v[78:81], v[18:33]
	v_mfma_f32_32x32x16_f16 v[2:17], v[86:89], v[66:69], v[2:17]
	v_lshl_add_u64 v[234:235], v[234:235], 0, s[2:3]
	ds_read_b128 v[66:69], v162 offset:64
	ds_read_b128 v[74:77], v163 offset:18496
	ds_read_b128 v[78:81], v162 offset:96
	ds_read_b128 v[82:85], v163 offset:18528
	ds_read_b128 v[86:89], v162 offset:4672
	ds_read_b128 v[178:181], v162 offset:4704
	s_waitcnt lgkmcnt(4)
	v_mfma_f32_32x32x16_f16 v[50:65], v[66:69], v[74:77], v[50:65]
	v_mfma_f32_32x32x16_f16 v[34:49], v[66:69], v[70:73], v[34:49]
	v_lshl_add_u64 v[238:239], v[238:239], 0, s[2:3]
	s_waitcnt lgkmcnt(1)
	v_mfma_f32_32x32x16_f16 v[18:33], v[86:89], v[74:77], v[18:33]
	v_mfma_f32_32x32x16_f16 v[2:17], v[86:89], v[70:73], v[2:17]
	v_lshl_add_u64 v[240:241], v[240:241], 0, s[2:3]
	v_mfma_f32_32x32x16_f16 v[50:65], v[78:81], v[82:85], v[50:65]
	v_mfma_f32_32x32x16_f16 v[34:49], v[78:81], v[174:177], v[34:49]
	v_lshl_add_u64 v[242:243], v[242:243], 0, s[2:3]
	s_waitcnt lgkmcnt(0)
	v_mfma_f32_32x32x16_f16 v[18:33], v[178:181], v[82:85], v[18:33]
	v_mfma_f32_32x32x16_f16 v[2:17], v[178:181], v[174:177], v[2:17]
	v_lshl_add_u64 v[244:245], v[244:245], 0, s[2:3]
	s_add_u32 s40, s40, 0x80
	s_addc_u32 s41, s41, 0
	s_cmpk_lg_i32 s40, 0x380
	s_cbranch_scc1 .LBB0_1743
	s_barrier
	s_waitcnt vmcnt(7)
	ds_write_b128 v172, v[192:195]
	s_waitcnt vmcnt(6)
	ds_write_b128 v172, v[196:199] offset:4608
	s_waitcnt vmcnt(5)
	ds_write_b128 v172, v[200:203] offset:9216
	s_waitcnt vmcnt(4)
	ds_write_b128 v172, v[204:207] offset:13824
	s_waitcnt vmcnt(3)
	ds_write_b128 v172, v[208:211] offset:18432
	s_waitcnt vmcnt(2)
	ds_write_b128 v172, v[212:215] offset:23040
	s_waitcnt vmcnt(1)
	ds_write_b128 v172, v[216:219] offset:27648
	s_waitcnt vmcnt(0)
	ds_write_b128 v172, v[220:223] offset:32256
	s_waitcnt lgkmcnt(0)
	s_barrier
	ds_read_b128 v[66:69], v162 offset:4608
	ds_read_b128 v[70:73], v171 offset:18432
	ds_read_b128 v[74:77], v162
	ds_read_b128 v[78:81], v162 offset:32
	ds_read_b128 v[82:85], v163 offset:18432
	ds_read_b128 v[86:89], v163 offset:18464
	s_waitcnt lgkmcnt(1)
	v_mfma_f32_32x32x16_f16 v[50:65], v[74:77], v[82:85], v[50:65]
	s_lshl_b32 s2, s56, 11
	s_add_u32 s2, s52, s2
	s_addc_u32 s3, s53, 0
	v_lshlrev_b32_e32 v0, 1, v0
	s_add_i32 s56, s56, 1
	s_add_u32 s38, s38, 0x100000
	s_addc_u32 s39, s39, 0
	v_mfma_f32_32x32x16_f16 v[34:49], v[74:77], v[70:73], v[34:49]
	s_cmp_lg_u32 s56, 3
	v_mfma_f32_32x32x16_f16 v[18:33], v[66:69], v[82:85], v[18:33]
	v_mfma_f32_32x32x16_f16 v[2:17], v[66:69], v[70:73], v[2:17]
	ds_read_b128 v[66:69], v162 offset:4640
	ds_read_b128 v[70:73], v163 offset:23072
	s_waitcnt lgkmcnt(2)
	v_mfma_f32_32x32x16_f16 v[50:65], v[78:81], v[86:89], v[50:65]
	s_waitcnt lgkmcnt(0)
	v_mfma_f32_32x32x16_f16 v[34:49], v[78:81], v[70:73], v[34:49]
	v_mfma_f32_32x32x16_f16 v[18:33], v[66:69], v[86:89], v[18:33]
	v_mfma_f32_32x32x16_f16 v[2:17], v[66:69], v[70:73], v[2:17]
	ds_read_b128 v[66:69], v162 offset:64
	ds_read_b128 v[70:73], v162 offset:4672
	ds_read_b128 v[74:77], v163 offset:18496
	ds_read_b128 v[78:81], v163 offset:23104
	s_waitcnt lgkmcnt(1)
	v_mfma_f32_32x32x16_f16 v[50:65], v[66:69], v[74:77], v[50:65]
	s_waitcnt lgkmcnt(0)
	v_mfma_f32_32x32x16_f16 v[34:49], v[66:69], v[78:81], v[34:49]
	v_mfma_f32_32x32x16_f16 v[18:33], v[70:73], v[74:77], v[18:33]
	v_mfma_f32_32x32x16_f16 v[2:17], v[70:73], v[78:81], v[2:17]
	ds_read_b128 v[66:69], v162 offset:96
	ds_read_b128 v[70:73], v162 offset:4704
	ds_read_b128 v[74:77], v163 offset:18528
	ds_read_b128 v[78:81], v163 offset:23136
	s_waitcnt lgkmcnt(1)
; __device__ __forceinline__ float sigmoidf_(float x) { return 1.f / (1.f + __expf(-x)); }
; template <int NI, class LA, class LB, class EP>
; __device__ __forceinline__ void gemm_tile(int K, LA loadA, LB loadB, EP epi, char* smem) {
;     ...
; #pragma unroll
;   for (int mi = 0; mi < 2; ++mi)
; #pragma unroll
;     for (int ni = 0; ni < NI; ++ni)
; #pragma unroll
;       for (int r = 0; r < 16; ++r) {
;         const int row = wm * 64 + mi * 32 + (r & 3) + 8 * (r >> 2) + 4 * (lane >> 5);
;         const int col = wn * (NI * 32) + ni * 32 + (lane & 31);
;         epi(mi, ni, r, row, col, acc[mi][ni][r]);
;       }
; __device__ __forceinline__ void phase_merge(const KP& p, char* smem, int* q, int xcc) {
;     ...
;           [&](int mi, int ni, int r, int row, int col, float v) {
;             const float gz = (float)G[(size_t)row * NU + col];
;             tot[mi][ni][r] += sigmoidf_(gz) * v;
;           },
	v_mfma_f32_32x32x16_f16 v[50:65], v[66:69], v[74:77], v[50:65]
	s_waitcnt lgkmcnt(0)
	v_mfma_f32_32x32x16_f16 v[34:49], v[66:69], v[78:81], v[34:49]
	v_mfma_f32_32x32x16_f16 v[18:33], v[70:73], v[74:77], v[18:33]
	v_mfma_f32_32x32x16_f16 v[2:17], v[70:73], v[78:81], v[2:17]
	v_mov_b32_e32 v228, 0x11fe4
	v_mov_b32_e32 v229, 0x100
	v_mov_b32_e32 v230, 2
	v_mov_b32_e32 v231, 0x3727c5ac
	v_mov_b32_e32 v232, 0x11fa0
	v_mov_b32_e32 v233, 0x80000
	v_mov_b32_e32 v234, 0x1d0000
	v_mov_b32_e32 v235, 0xa800
	v_mov_b32_e32 v238, 0x4000
	v_mov_b32_e32 v239, 0x4400
	v_mov_b32_e32 v240, 0x4800
	v_mov_b32_e32 v241, 0x4c00
	v_mov_b32_e32 v242, 0xf149f2ca
	v_mov_b32_e32 v243, 0x200
	v_mov_b32_e32 v244, 0x400
	v_mov_b32_e32 v245, 0x600
	v_lshrrev_b32_e32 v94, 7, v224
	v_lshlrev_b32_e32 v94, 4, v94
	v_bfe_u32 v95, v224, 5, 1
	v_add_u32_e32 v94, v94, v95
	v_mul_u32_u24_e32 v94, 0xe800, v94
	v_bfe_u32 v95, v224, 6, 1
	v_lshl_add_u32 v94, v95, 7, v94
	v_and_b32_e32 v95, 31, v224
	v_lshl_add_u32 v94, v95, 1, v94
	s_mov_b64 s[40:41], s[2:3]
	v_mov_b32_e32 v96, v94
	global_load_ushort v192, v96, s[40:41]
	v_add_u32_e32 v96, 0x3a00, v94
	global_load_ushort v193, v96, s[40:41]
	v_add_u32_e32 v96, 0x7400, v94
	global_load_ushort v194, v96, s[40:41]
	v_add_u32_e32 v96, 0xae00, v94
	global_load_ushort v195, v96, s[40:41]
	v_add_u32_e32 v96, 0x1d000, v94
	global_load_ushort v196, v96, s[40:41]
	v_add_u32_e32 v96, 0x20a00, v94
	global_load_ushort v197, v96, s[40:41]
	v_add_u32_e32 v96, 0x24400, v94
	global_load_ushort v198, v96, s[40:41]
	v_add_u32_e32 v96, 0x27e00, v94
	global_load_ushort v199, v96, s[40:41]
	v_add_u32_e32 v96, 0x3a000, v94
	global_load_ushort v200, v96, s[40:41]
	v_add_u32_e32 v96, 0x3da00, v94
	global_load_ushort v201, v96, s[40:41]
	v_add_u32_e32 v96, 0x41400, v94
	global_load_ushort v202, v96, s[40:41]
	v_add_u32_e32 v96, 0x44e00, v94
	global_load_ushort v203, v96, s[40:41]
	v_add_u32_e32 v96, 0x57000, v94
	global_load_ushort v204, v96, s[40:41]
	v_add_u32_e32 v96, 0x5aa00, v94
	global_load_ushort v205, v96, s[40:41]
	v_add_u32_e32 v96, 0x5e400, v94
	global_load_ushort v206, v96, s[40:41]
	v_add_u32_e32 v96, 0x61e00, v94
	global_load_ushort v207, v96, s[40:41]
	v_mov_b32_e32 v96, v94
	global_load_ushort v208, v96, s[40:41] offset:64
	v_add_u32_e32 v96, 0x3a00, v94
	global_load_ushort v209, v96, s[40:41] offset:64
	v_add_u32_e32 v96, 0x7400, v94
	global_load_ushort v210, v96, s[40:41] offset:64
	v_add_u32_e32 v96, 0xae00, v94
	global_load_ushort v211, v96, s[40:41] offset:64
	v_add_u32_e32 v96, 0x1d000, v94
	global_load_ushort v212, v96, s[40:41] offset:64
	v_add_u32_e32 v96, 0x20a00, v94
	global_load_ushort v213, v96, s[40:41] offset:64
	v_add_u32_e32 v96, 0x24400, v94
	global_load_ushort v214, v96, s[40:41] offset:64
	v_add_u32_e32 v96, 0x27e00, v94
	global_load_ushort v215, v96, s[40:41] offset:64
	v_add_u32_e32 v96, 0x3a000, v94
	global_load_ushort v216, v96, s[40:41] offset:64
	v_add_u32_e32 v96, 0x3da00, v94
	global_load_ushort v217, v96, s[40:41] offset:64
	v_add_u32_e32 v96, 0x41400, v94
	global_load_ushort v218, v96, s[40:41] offset:64
	v_add_u32_e32 v96, 0x44e00, v94
	global_load_ushort v219, v96, s[40:41] offset:64
	v_add_u32_e32 v96, 0x57000, v94
	global_load_ushort v220, v96, s[40:41] offset:64
	v_add_u32_e32 v96, 0x5aa00, v94
	global_load_ushort v221, v96, s[40:41] offset:64
	v_add_u32_e32 v96, 0x5e400, v94
	global_load_ushort v222, v96, s[40:41] offset:64
	v_add_u32_e32 v96, 0x61e00, v94
	global_load_ushort v223, v96, s[40:41] offset:64
	s_nop 7
	s_waitcnt vmcnt(30)
	v_cvt_f32_f16_e32 v68, v192
	v_cvt_f32_f16_e32 v69, v193
	v_add_u32_e32 v96, 0x74000, v94
	global_load_ushort v192, v96, s[40:41]
	v_add_u32_e32 v96, 0x77a00, v94
	global_load_ushort v193, v96, s[40:41]
	v_mul_f32_e32 v68, 0xbfb8aa3b, v68
	v_mul_f32_e32 v69, 0xbfb8aa3b, v69
	v_exp_f32_e32 v68, v68
	v_exp_f32_e32 v69, v69
	s_nop 0
	v_pk_add_f32 v[68:69], v[68:69], 1.0 op_sel_hi:[1,0]
	s_nop 0
	v_div_scale_f32 v70, s[2:3], v69, v69, 1.0
	v_rcp_f32_e32 v71, v70
	s_nop 0
	v_fma_f32 v72, -v70, v71, 1.0
	v_fmac_f32_e32 v71, v72, v71
	v_div_scale_f32 v72, vcc, 1.0, v69, 1.0
	v_mul_f32_e32 v73, v72, v71
	v_fma_f32 v74, -v70, v73, v72
	v_fmac_f32_e32 v73, v74, v71
	v_fma_f32 v70, -v70, v73, v72
	v_div_fmas_f32 v70, v70, v71, v73
	v_div_fixup_f32 v69, v70, v69, 1.0
	v_div_scale_f32 v70, s[2:3], v68, v68, 1.0
	v_rcp_f32_e32 v71, v70
	s_nop 0
	v_fma_f32 v72, -v70, v71, 1.0
	v_fmac_f32_e32 v71, v72, v71
	v_div_scale_f32 v72, vcc, 1.0, v68, 1.0
	v_mul_f32_e32 v73, v72, v71
	v_fma_f32 v74, -v70, v73, v72
	v_fmac_f32_e32 v73, v74, v71
	v_fma_f32 v70, -v70, v73, v72
	v_div_fmas_f32 v70, v70, v71, v73
	v_div_fixup_f32 v68, v70, v68, 1.0
	v_pk_fma_f32 v[160:161], v[50:51], v[68:69], v[160:161]
	s_waitcnt vmcnt(30)
	v_cvt_f32_f16_e32 v68, v194
	v_cvt_f32_f16_e32 v69, v195
	v_add_u32_e32 v96, 0x7b400, v94
	global_load_ushort v194, v96, s[40:41]
	v_add_u32_e32 v96, 0x7ee00, v94
	global_load_ushort v195, v96, s[40:41]
	v_mul_f32_e32 v68, 0xbfb8aa3b, v68
	v_mul_f32_e32 v69, 0xbfb8aa3b, v69
	v_exp_f32_e32 v68, v68
	v_exp_f32_e32 v69, v69
	s_nop 0
	v_pk_add_f32 v[68:69], v[68:69], 1.0 op_sel_hi:[1,0]
	s_nop 0
	v_div_scale_f32 v70, s[2:3], v69, v69, 1.0
	v_rcp_f32_e32 v71, v70
	s_nop 0
	v_fma_f32 v72, -v70, v71, 1.0
	v_fmac_f32_e32 v71, v72, v71
	v_div_scale_f32 v72, vcc, 1.0, v69, 1.0
	v_mul_f32_e32 v73, v72, v71
	v_fma_f32 v74, -v70, v73, v72
	v_fmac_f32_e32 v73, v74, v71
	v_fma_f32 v70, -v70, v73, v72
	v_div_fmas_f32 v70, v70, v71, v73
	v_div_fixup_f32 v69, v70, v69, 1.0
	v_div_scale_f32 v70, s[2:3], v68, v68, 1.0
	v_rcp_f32_e32 v71, v70
	s_nop 0
	v_fma_f32 v72, -v70, v71, 1.0
	v_fmac_f32_e32 v71, v72, v71
	v_div_scale_f32 v72, vcc, 1.0, v68, 1.0
	v_mul_f32_e32 v73, v72, v71
	v_fma_f32 v74, -v70, v73, v72
	v_fmac_f32_e32 v73, v74, v71
	v_fma_f32 v70, -v70, v73, v72
	v_div_fmas_f32 v70, v70, v71, v73
	v_div_fixup_f32 v68, v70, v68, 1.0
	v_pk_fma_f32 v[158:159], v[52:53], v[68:69], v[158:159]
	s_waitcnt vmcnt(30)
; __device__ __forceinline__ float sigmoidf_(float x) { return 1.f / (1.f + __expf(-x)); }
; __device__ __forceinline__ void phase_merge(const KP& p, char* smem, int* q, int xcc) {
;     ...
;           [&](int mi, int ni, int r, int row, int col, float v) {
;             const float gz = (float)G[(size_t)row * NU + col];
;             tot[mi][ni][r] += sigmoidf_(gz) * v;
;           },
	v_cvt_f32_f16_e32 v68, v196
	v_cvt_f32_f16_e32 v69, v197
	v_add_u32_e32 v96, 0x91000, v94
	global_load_ushort v196, v96, s[40:41]
	v_add_u32_e32 v96, 0x94a00, v94
	global_load_ushort v197, v96, s[40:41]
	v_mul_f32_e32 v68, 0xbfb8aa3b, v68
	v_mul_f32_e32 v69, 0xbfb8aa3b, v69
	v_exp_f32_e32 v68, v68
	v_exp_f32_e32 v69, v69
	s_nop 0
	v_pk_add_f32 v[68:69], v[68:69], 1.0 op_sel_hi:[1,0]
	s_nop 0
	v_div_scale_f32 v70, s[2:3], v69, v69, 1.0
	v_rcp_f32_e32 v71, v70
	s_nop 0
	v_fma_f32 v72, -v70, v71, 1.0
	v_fmac_f32_e32 v71, v72, v71
	v_div_scale_f32 v72, vcc, 1.0, v69, 1.0
	v_mul_f32_e32 v73, v72, v71
	v_fma_f32 v74, -v70, v73, v72
	v_fmac_f32_e32 v73, v74, v71
	v_fma_f32 v70, -v70, v73, v72
	v_div_fmas_f32 v70, v70, v71, v73
	v_div_fixup_f32 v69, v70, v69, 1.0
	v_div_scale_f32 v70, s[2:3], v68, v68, 1.0
	v_rcp_f32_e32 v71, v70
	s_nop 0
	v_fma_f32 v72, -v70, v71, 1.0
	v_fmac_f32_e32 v71, v72, v71
	v_div_scale_f32 v72, vcc, 1.0, v68, 1.0
	v_mul_f32_e32 v73, v72, v71
	v_fma_f32 v74, -v70, v73, v72
	v_fmac_f32_e32 v73, v74, v71
	v_fma_f32 v70, -v70, v73, v72
	v_div_fmas_f32 v70, v70, v71, v73
	v_div_fixup_f32 v68, v70, v68, 1.0
	v_pk_fma_f32 v[156:157], v[54:55], v[68:69], v[156:157]
	s_waitcnt vmcnt(30)
	v_cvt_f32_f16_e32 v68, v198
	v_cvt_f32_f16_e32 v69, v199
	v_add_u32_e32 v96, 0x98400, v94
	global_load_ushort v198, v96, s[40:41]
	v_add_u32_e32 v96, 0x9be00, v94
	global_load_ushort v199, v96, s[40:41]
	v_mul_f32_e32 v68, 0xbfb8aa3b, v68
	v_mul_f32_e32 v69, 0xbfb8aa3b, v69
	v_exp_f32_e32 v68, v68
	v_exp_f32_e32 v69, v69
	s_nop 0
	v_pk_add_f32 v[68:69], v[68:69], 1.0 op_sel_hi:[1,0]
	s_nop 0
	v_div_scale_f32 v70, s[2:3], v69, v69, 1.0
	v_rcp_f32_e32 v71, v70
	s_nop 0
	v_fma_f32 v72, -v70, v71, 1.0
	v_fmac_f32_e32 v71, v72, v71
	v_div_scale_f32 v72, vcc, 1.0, v69, 1.0
	v_mul_f32_e32 v73, v72, v71
	v_fma_f32 v74, -v70, v73, v72
	v_fmac_f32_e32 v73, v74, v71
	v_fma_f32 v70, -v70, v73, v72
	v_div_fmas_f32 v70, v70, v71, v73
	v_div_fixup_f32 v69, v70, v69, 1.0
	v_div_scale_f32 v70, s[2:3], v68, v68, 1.0
	v_rcp_f32_e32 v71, v70
	s_nop 0
	v_fma_f32 v72, -v70, v71, 1.0
	v_fmac_f32_e32 v71, v72, v71
	v_div_scale_f32 v72, vcc, 1.0, v68, 1.0
	v_mul_f32_e32 v73, v72, v71
	v_fma_f32 v74, -v70, v73, v72
	v_fmac_f32_e32 v73, v74, v71
	v_fma_f32 v70, -v70, v73, v72
	v_div_fmas_f32 v70, v70, v71, v73
	v_div_fixup_f32 v68, v70, v68, 1.0
	v_pk_fma_f32 v[154:155], v[56:57], v[68:69], v[154:155]
	s_waitcnt vmcnt(30)
	v_cvt_f32_f16_e32 v68, v200
	v_cvt_f32_f16_e32 v69, v201
	v_add_u32_e32 v96, 0xae000, v94
	global_load_ushort v200, v96, s[40:41]
	v_add_u32_e32 v96, 0xb1a00, v94
	global_load_ushort v201, v96, s[40:41]
	v_mul_f32_e32 v68, 0xbfb8aa3b, v68
	v_mul_f32_e32 v69, 0xbfb8aa3b, v69
	v_exp_f32_e32 v68, v68
	v_exp_f32_e32 v69, v69
	s_nop 0
	v_pk_add_f32 v[68:69], v[68:69], 1.0 op_sel_hi:[1,0]
	s_nop 0
	v_div_scale_f32 v70, s[2:3], v69, v69, 1.0
	v_rcp_f32_e32 v71, v70
	s_nop 0
	v_fma_f32 v72, -v70, v71, 1.0
	v_fmac_f32_e32 v71, v72, v71
	v_div_scale_f32 v72, vcc, 1.0, v69, 1.0
	v_mul_f32_e32 v73, v72, v71
	v_fma_f32 v74, -v70, v73, v72
	v_fmac_f32_e32 v73, v74, v71
	v_fma_f32 v70, -v70, v73, v72
	v_div_fmas_f32 v70, v70, v71, v73
	v_div_fixup_f32 v69, v70, v69, 1.0
	v_div_scale_f32 v70, s[2:3], v68, v68, 1.0
	v_rcp_f32_e32 v71, v70
	s_nop 0
	v_fma_f32 v72, -v70, v71, 1.0
	v_fmac_f32_e32 v71, v72, v71
	v_div_scale_f32 v72, vcc, 1.0, v68, 1.0
	v_mul_f32_e32 v73, v72, v71
	v_fma_f32 v74, -v70, v73, v72
	v_fmac_f32_e32 v73, v74, v71
	v_fma_f32 v70, -v70, v73, v72
	v_div_fmas_f32 v70, v70, v71, v73
	v_div_fixup_f32 v68, v70, v68, 1.0
	v_pk_fma_f32 v[152:153], v[58:59], v[68:69], v[152:153]
	s_waitcnt vmcnt(30)
	v_cvt_f32_f16_e32 v68, v202
	v_cvt_f32_f16_e32 v69, v203
	v_add_u32_e32 v96, 0xb5400, v94
	global_load_ushort v202, v96, s[40:41]
	v_add_u32_e32 v96, 0xb8e00, v94
	global_load_ushort v203, v96, s[40:41]
	v_mul_f32_e32 v68, 0xbfb8aa3b, v68
	v_mul_f32_e32 v69, 0xbfb8aa3b, v69
	v_exp_f32_e32 v68, v68
	v_exp_f32_e32 v69, v69
	s_nop 0
	v_pk_add_f32 v[68:69], v[68:69], 1.0 op_sel_hi:[1,0]
	s_nop 0
	v_div_scale_f32 v70, s[2:3], v69, v69, 1.0
	v_rcp_f32_e32 v71, v70
	s_nop 0
	v_fma_f32 v72, -v70, v71, 1.0
	v_fmac_f32_e32 v71, v72, v71
	v_div_scale_f32 v72, vcc, 1.0, v69, 1.0
	v_mul_f32_e32 v73, v72, v71
	v_fma_f32 v74, -v70, v73, v72
	v_fmac_f32_e32 v73, v74, v71
	v_fma_f32 v70, -v70, v73, v72
	v_div_fmas_f32 v70, v70, v71, v73
	v_div_fixup_f32 v69, v70, v69, 1.0
	v_div_scale_f32 v70, s[2:3], v68, v68, 1.0
	v_rcp_f32_e32 v71, v70
	s_nop 0
	v_fma_f32 v72, -v70, v71, 1.0
	v_fmac_f32_e32 v71, v72, v71
	v_div_scale_f32 v72, vcc, 1.0, v68, 1.0
	v_mul_f32_e32 v73, v72, v71
	v_fma_f32 v74, -v70, v73, v72
	v_fmac_f32_e32 v73, v74, v71
	v_fma_f32 v70, -v70, v73, v72
	v_div_fmas_f32 v70, v70, v71, v73
	v_div_fixup_f32 v68, v70, v68, 1.0
	v_pk_fma_f32 v[150:151], v[60:61], v[68:69], v[150:151]
	s_waitcnt vmcnt(30)
	v_cvt_f32_f16_e32 v68, v204
	v_cvt_f32_f16_e32 v69, v205
	v_add_u32_e32 v96, 0xcb000, v94
	global_load_ushort v204, v96, s[40:41]
	v_add_u32_e32 v96, 0xcea00, v94
	global_load_ushort v205, v96, s[40:41]
	v_mul_f32_e32 v68, 0xbfb8aa3b, v68
	v_mul_f32_e32 v69, 0xbfb8aa3b, v69
	v_exp_f32_e32 v68, v68
	v_exp_f32_e32 v69, v69
	s_nop 0
	v_pk_add_f32 v[68:69], v[68:69], 1.0 op_sel_hi:[1,0]
	s_nop 0
	v_div_scale_f32 v70, s[2:3], v69, v69, 1.0
	v_rcp_f32_e32 v71, v70
	s_nop 0
	v_fma_f32 v72, -v70, v71, 1.0
	v_fmac_f32_e32 v71, v72, v71
	v_div_scale_f32 v72, vcc, 1.0, v69, 1.0
	v_mul_f32_e32 v73, v72, v71
	v_fma_f32 v74, -v70, v73, v72
	v_fmac_f32_e32 v73, v74, v71
	v_fma_f32 v70, -v70, v73, v72
	v_div_fmas_f32 v70, v70, v71, v73
	v_div_fixup_f32 v69, v70, v69, 1.0
	v_div_scale_f32 v70, s[2:3], v68, v68, 1.0
	v_rcp_f32_e32 v71, v70
	s_nop 0
	v_fma_f32 v72, -v70, v71, 1.0
	v_fmac_f32_e32 v71, v72, v71
	v_div_scale_f32 v72, vcc, 1.0, v68, 1.0
	v_mul_f32_e32 v73, v72, v71
	v_fma_f32 v74, -v70, v73, v72
	v_fmac_f32_e32 v73, v74, v71
	v_fma_f32 v70, -v70, v73, v72
	v_div_fmas_f32 v70, v70, v71, v73
	v_div_fixup_f32 v68, v70, v68, 1.0
	v_pk_fma_f32 v[148:149], v[62:63], v[68:69], v[148:149]
	s_waitcnt vmcnt(30)
; __device__ __forceinline__ float sigmoidf_(float x) { return 1.f / (1.f + __expf(-x)); }
; __device__ __forceinline__ void phase_merge(const KP& p, char* smem, int* q, int xcc) {
;     ...
;           [&](int mi, int ni, int r, int row, int col, float v) {
;             const float gz = (float)G[(size_t)row * NU + col];
;             tot[mi][ni][r] += sigmoidf_(gz) * v;
;           },
	v_cvt_f32_f16_e32 v68, v206
	v_cvt_f32_f16_e32 v69, v207
	v_add_u32_e32 v96, 0xd2400, v94
	global_load_ushort v206, v96, s[40:41]
	v_add_u32_e32 v96, 0xd5e00, v94
	global_load_ushort v207, v96, s[40:41]
	v_mul_f32_e32 v68, 0xbfb8aa3b, v68
	v_mul_f32_e32 v69, 0xbfb8aa3b, v69
	v_exp_f32_e32 v68, v68
	v_exp_f32_e32 v69, v69
	s_nop 0
	v_pk_add_f32 v[68:69], v[68:69], 1.0 op_sel_hi:[1,0]
	s_nop 0
	v_div_scale_f32 v70, s[2:3], v69, v69, 1.0
	v_rcp_f32_e32 v71, v70
	s_nop 0
	v_fma_f32 v72, -v70, v71, 1.0
	v_fmac_f32_e32 v71, v72, v71
	v_div_scale_f32 v72, vcc, 1.0, v69, 1.0
	v_mul_f32_e32 v73, v72, v71
	v_fma_f32 v74, -v70, v73, v72
	v_fmac_f32_e32 v73, v74, v71
	v_fma_f32 v70, -v70, v73, v72
	v_div_fmas_f32 v70, v70, v71, v73
	v_div_fixup_f32 v69, v70, v69, 1.0
	v_div_scale_f32 v70, s[2:3], v68, v68, 1.0
	v_rcp_f32_e32 v71, v70
	s_nop 0
	v_fma_f32 v72, -v70, v71, 1.0
	v_fmac_f32_e32 v71, v72, v71
	v_div_scale_f32 v72, vcc, 1.0, v68, 1.0
	v_mul_f32_e32 v73, v72, v71
	v_fma_f32 v74, -v70, v73, v72
	v_fmac_f32_e32 v73, v74, v71
	v_fma_f32 v70, -v70, v73, v72
	v_div_fmas_f32 v70, v70, v71, v73
	v_div_fixup_f32 v68, v70, v68, 1.0
	v_pk_fma_f32 v[146:147], v[64:65], v[68:69], v[146:147]
	s_waitcnt vmcnt(30)
	v_cvt_f32_f16_e32 v68, v208
	v_cvt_f32_f16_e32 v69, v209
	v_add_u32_e32 v96, 0x74000, v94
	global_load_ushort v208, v96, s[40:41] offset:64
	v_add_u32_e32 v96, 0x77a00, v94
	global_load_ushort v209, v96, s[40:41] offset:64
	v_mul_f32_e32 v68, 0xbfb8aa3b, v68
	v_mul_f32_e32 v69, 0xbfb8aa3b, v69
	v_exp_f32_e32 v68, v68
	v_exp_f32_e32 v69, v69
	s_nop 0
	v_pk_add_f32 v[68:69], v[68:69], 1.0 op_sel_hi:[1,0]
	s_nop 0
	v_div_scale_f32 v70, s[2:3], v69, v69, 1.0
	v_rcp_f32_e32 v71, v70
	s_nop 0
	v_fma_f32 v72, -v70, v71, 1.0
	v_fmac_f32_e32 v71, v72, v71
	v_div_scale_f32 v72, vcc, 1.0, v69, 1.0
	v_mul_f32_e32 v73, v72, v71
	v_fma_f32 v74, -v70, v73, v72
	v_fmac_f32_e32 v73, v74, v71
	v_fma_f32 v70, -v70, v73, v72
	v_div_fmas_f32 v70, v70, v71, v73
	v_div_fixup_f32 v69, v70, v69, 1.0
	v_div_scale_f32 v70, s[2:3], v68, v68, 1.0
	v_rcp_f32_e32 v71, v70
	s_nop 0
	v_fma_f32 v72, -v70, v71, 1.0
	v_fmac_f32_e32 v71, v72, v71
	v_div_scale_f32 v72, vcc, 1.0, v68, 1.0
	v_mul_f32_e32 v73, v72, v71
	v_fma_f32 v74, -v70, v73, v72
	v_fmac_f32_e32 v73, v74, v71
	v_fma_f32 v70, -v70, v73, v72
	v_div_fmas_f32 v70, v70, v71, v73
	v_div_fixup_f32 v68, v70, v68, 1.0
	v_pk_fma_f32 v[144:145], v[34:35], v[68:69], v[144:145]
	s_waitcnt vmcnt(30)
	v_cvt_f32_f16_e32 v68, v210
	v_cvt_f32_f16_e32 v69, v211
	v_add_u32_e32 v96, 0x7b400, v94
	global_load_ushort v210, v96, s[40:41] offset:64
	v_add_u32_e32 v96, 0x7ee00, v94
	global_load_ushort v211, v96, s[40:41] offset:64
	v_mul_f32_e32 v68, 0xbfb8aa3b, v68
	v_mul_f32_e32 v69, 0xbfb8aa3b, v69
	v_exp_f32_e32 v68, v68
	v_exp_f32_e32 v69, v69
	s_nop 0
	v_pk_add_f32 v[68:69], v[68:69], 1.0 op_sel_hi:[1,0]
	s_nop 0
	v_div_scale_f32 v70, s[2:3], v69, v69, 1.0
	v_rcp_f32_e32 v71, v70
	s_nop 0
	v_fma_f32 v72, -v70, v71, 1.0
	v_fmac_f32_e32 v71, v72, v71
	v_div_scale_f32 v72, vcc, 1.0, v69, 1.0
	v_mul_f32_e32 v73, v72, v71
	v_fma_f32 v74, -v70, v73, v72
	v_fmac_f32_e32 v73, v74, v71
	v_fma_f32 v70, -v70, v73, v72
	v_div_fmas_f32 v70, v70, v71, v73
	v_div_fixup_f32 v69, v70, v69, 1.0
	v_div_scale_f32 v70, s[2:3], v68, v68, 1.0
	v_rcp_f32_e32 v71, v70
	s_nop 0
	v_fma_f32 v72, -v70, v71, 1.0
	v_fmac_f32_e32 v71, v72, v71
	v_div_scale_f32 v72, vcc, 1.0, v68, 1.0
	v_mul_f32_e32 v73, v72, v71
	v_fma_f32 v74, -v70, v73, v72
	v_fmac_f32_e32 v73, v74, v71
	v_fma_f32 v70, -v70, v73, v72
	v_div_fmas_f32 v70, v70, v71, v73
	v_div_fixup_f32 v68, v70, v68, 1.0
	v_pk_fma_f32 v[142:143], v[36:37], v[68:69], v[142:143]
	s_waitcnt vmcnt(30)
	v_cvt_f32_f16_e32 v68, v212
	v_cvt_f32_f16_e32 v69, v213
	v_add_u32_e32 v96, 0x91000, v94
	global_load_ushort v212, v96, s[40:41] offset:64
	v_add_u32_e32 v96, 0x94a00, v94
	global_load_ushort v213, v96, s[40:41] offset:64
	v_mul_f32_e32 v68, 0xbfb8aa3b, v68
	v_mul_f32_e32 v69, 0xbfb8aa3b, v69
	v_exp_f32_e32 v68, v68
	v_exp_f32_e32 v69, v69
	s_nop 0
	v_pk_add_f32 v[68:69], v[68:69], 1.0 op_sel_hi:[1,0]
	s_nop 0
	v_div_scale_f32 v70, s[2:3], v69, v69, 1.0
	v_rcp_f32_e32 v71, v70
	s_nop 0
	v_fma_f32 v72, -v70, v71, 1.0
	v_fmac_f32_e32 v71, v72, v71
	v_div_scale_f32 v72, vcc, 1.0, v69, 1.0
	v_mul_f32_e32 v73, v72, v71
	v_fma_f32 v74, -v70, v73, v72
	v_fmac_f32_e32 v73, v74, v71
	v_fma_f32 v70, -v70, v73, v72
	v_div_fmas_f32 v70, v70, v71, v73
	v_div_fixup_f32 v69, v70, v69, 1.0
	v_div_scale_f32 v70, s[2:3], v68, v68, 1.0
	v_rcp_f32_e32 v71, v70
	s_nop 0
	v_fma_f32 v72, -v70, v71, 1.0
	v_fmac_f32_e32 v71, v72, v71
	v_div_scale_f32 v72, vcc, 1.0, v68, 1.0
	v_mul_f32_e32 v73, v72, v71
	v_fma_f32 v74, -v70, v73, v72
	v_fmac_f32_e32 v73, v74, v71
	v_fma_f32 v70, -v70, v73, v72
	v_div_fmas_f32 v70, v70, v71, v73
	v_div_fixup_f32 v68, v70, v68, 1.0
	v_pk_fma_f32 v[140:141], v[38:39], v[68:69], v[140:141]
	s_waitcnt vmcnt(30)
	v_cvt_f32_f16_e32 v68, v214
	v_cvt_f32_f16_e32 v69, v215
	v_add_u32_e32 v96, 0x98400, v94
	global_load_ushort v214, v96, s[40:41] offset:64
	v_add_u32_e32 v96, 0x9be00, v94
	global_load_ushort v215, v96, s[40:41] offset:64
	v_mul_f32_e32 v68, 0xbfb8aa3b, v68
	v_mul_f32_e32 v69, 0xbfb8aa3b, v69
	v_exp_f32_e32 v68, v68
	v_exp_f32_e32 v69, v69
	s_nop 0
	v_pk_add_f32 v[68:69], v[68:69], 1.0 op_sel_hi:[1,0]
	s_nop 0
	v_div_scale_f32 v70, s[2:3], v69, v69, 1.0
	v_rcp_f32_e32 v71, v70
	s_nop 0
	v_fma_f32 v72, -v70, v71, 1.0
	v_fmac_f32_e32 v71, v72, v71
	v_div_scale_f32 v72, vcc, 1.0, v69, 1.0
	v_mul_f32_e32 v73, v72, v71
	v_fma_f32 v74, -v70, v73, v72
	v_fmac_f32_e32 v73, v74, v71
	v_fma_f32 v70, -v70, v73, v72
	v_div_fmas_f32 v70, v70, v71, v73
	v_div_fixup_f32 v69, v70, v69, 1.0
	v_div_scale_f32 v70, s[2:3], v68, v68, 1.0
	v_rcp_f32_e32 v71, v70
	s_nop 0
	v_fma_f32 v72, -v70, v71, 1.0
	v_fmac_f32_e32 v71, v72, v71
	v_div_scale_f32 v72, vcc, 1.0, v68, 1.0
	v_mul_f32_e32 v73, v72, v71
	v_fma_f32 v74, -v70, v73, v72
	v_fmac_f32_e32 v73, v74, v71
	v_fma_f32 v70, -v70, v73, v72
	v_div_fmas_f32 v70, v70, v71, v73
	v_div_fixup_f32 v68, v70, v68, 1.0
	v_pk_fma_f32 v[138:139], v[40:41], v[68:69], v[138:139]
	s_waitcnt vmcnt(30)
; __device__ __forceinline__ float sigmoidf_(float x) { return 1.f / (1.f + __expf(-x)); }
; __device__ __forceinline__ void phase_merge(const KP& p, char* smem, int* q, int xcc) {
;     ...
;           [&](int mi, int ni, int r, int row, int col, float v) {
;             const float gz = (float)G[(size_t)row * NU + col];
;             tot[mi][ni][r] += sigmoidf_(gz) * v;
;           },
	v_cvt_f32_f16_e32 v68, v216
	v_cvt_f32_f16_e32 v69, v217
	v_add_u32_e32 v96, 0xae000, v94
	global_load_ushort v216, v96, s[40:41] offset:64
	v_add_u32_e32 v96, 0xb1a00, v94
	global_load_ushort v217, v96, s[40:41] offset:64
	v_mul_f32_e32 v68, 0xbfb8aa3b, v68
	v_mul_f32_e32 v69, 0xbfb8aa3b, v69
	v_exp_f32_e32 v68, v68
	v_exp_f32_e32 v69, v69
	s_nop 0
	v_pk_add_f32 v[68:69], v[68:69], 1.0 op_sel_hi:[1,0]
	s_nop 0
	v_div_scale_f32 v70, s[2:3], v69, v69, 1.0
	v_rcp_f32_e32 v71, v70
	s_nop 0
	v_fma_f32 v72, -v70, v71, 1.0
	v_fmac_f32_e32 v71, v72, v71
	v_div_scale_f32 v72, vcc, 1.0, v69, 1.0
	v_mul_f32_e32 v73, v72, v71
	v_fma_f32 v74, -v70, v73, v72
	v_fmac_f32_e32 v73, v74, v71
	v_fma_f32 v70, -v70, v73, v72
	v_div_fmas_f32 v70, v70, v71, v73
	v_div_fixup_f32 v69, v70, v69, 1.0
	v_div_scale_f32 v70, s[2:3], v68, v68, 1.0
	v_rcp_f32_e32 v71, v70
	s_nop 0
	v_fma_f32 v72, -v70, v71, 1.0
	v_fmac_f32_e32 v71, v72, v71
	v_div_scale_f32 v72, vcc, 1.0, v68, 1.0
	v_mul_f32_e32 v73, v72, v71
	v_fma_f32 v74, -v70, v73, v72
	v_fmac_f32_e32 v73, v74, v71
	v_fma_f32 v70, -v70, v73, v72
	v_div_fmas_f32 v70, v70, v71, v73
	v_div_fixup_f32 v68, v70, v68, 1.0
	v_pk_fma_f32 v[136:137], v[42:43], v[68:69], v[136:137]
	s_waitcnt vmcnt(30)
	v_cvt_f32_f16_e32 v68, v218
	v_cvt_f32_f16_e32 v69, v219
	v_add_u32_e32 v96, 0xb5400, v94
	global_load_ushort v218, v96, s[40:41] offset:64
	v_add_u32_e32 v96, 0xb8e00, v94
	global_load_ushort v219, v96, s[40:41] offset:64
	v_mul_f32_e32 v68, 0xbfb8aa3b, v68
	v_mul_f32_e32 v69, 0xbfb8aa3b, v69
	v_exp_f32_e32 v68, v68
	v_exp_f32_e32 v69, v69
	s_nop 0
	v_pk_add_f32 v[68:69], v[68:69], 1.0 op_sel_hi:[1,0]
	s_nop 0
	v_div_scale_f32 v70, s[2:3], v69, v69, 1.0
	v_rcp_f32_e32 v71, v70
	s_nop 0
	v_fma_f32 v72, -v70, v71, 1.0
	v_fmac_f32_e32 v71, v72, v71
	v_div_scale_f32 v72, vcc, 1.0, v69, 1.0
	v_mul_f32_e32 v73, v72, v71
	v_fma_f32 v74, -v70, v73, v72
	v_fmac_f32_e32 v73, v74, v71
	v_fma_f32 v70, -v70, v73, v72
	v_div_fmas_f32 v70, v70, v71, v73
	v_div_fixup_f32 v69, v70, v69, 1.0
	v_div_scale_f32 v70, s[2:3], v68, v68, 1.0
	v_rcp_f32_e32 v71, v70
	s_nop 0
	v_fma_f32 v72, -v70, v71, 1.0
	v_fmac_f32_e32 v71, v72, v71
	v_div_scale_f32 v72, vcc, 1.0, v68, 1.0
	v_mul_f32_e32 v73, v72, v71
	v_fma_f32 v74, -v70, v73, v72
	v_fmac_f32_e32 v73, v74, v71
	v_fma_f32 v70, -v70, v73, v72
	v_div_fmas_f32 v70, v70, v71, v73
	v_div_fixup_f32 v68, v70, v68, 1.0
	v_pk_fma_f32 v[134:135], v[44:45], v[68:69], v[134:135]
	s_waitcnt vmcnt(30)
	v_cvt_f32_f16_e32 v68, v220
	v_cvt_f32_f16_e32 v69, v221
	v_add_u32_e32 v96, 0xcb000, v94
	global_load_ushort v220, v96, s[40:41] offset:64
	v_add_u32_e32 v96, 0xcea00, v94
	global_load_ushort v221, v96, s[40:41] offset:64
	v_mul_f32_e32 v68, 0xbfb8aa3b, v68
	v_mul_f32_e32 v69, 0xbfb8aa3b, v69
	v_exp_f32_e32 v68, v68
	v_exp_f32_e32 v69, v69
	s_nop 0
	v_pk_add_f32 v[68:69], v[68:69], 1.0 op_sel_hi:[1,0]
	s_nop 0
	v_div_scale_f32 v70, s[2:3], v69, v69, 1.0
	v_rcp_f32_e32 v71, v70
	s_nop 0
	v_fma_f32 v72, -v70, v71, 1.0
	v_fmac_f32_e32 v71, v72, v71
	v_div_scale_f32 v72, vcc, 1.0, v69, 1.0
	v_mul_f32_e32 v73, v72, v71
	v_fma_f32 v74, -v70, v73, v72
	v_fmac_f32_e32 v73, v74, v71
	v_fma_f32 v70, -v70, v73, v72
	v_div_fmas_f32 v70, v70, v71, v73
	v_div_fixup_f32 v69, v70, v69, 1.0
	v_div_scale_f32 v70, s[2:3], v68, v68, 1.0
	v_rcp_f32_e32 v71, v70
	s_nop 0
	v_fma_f32 v72, -v70, v71, 1.0
	v_fmac_f32_e32 v71, v72, v71
	v_div_scale_f32 v72, vcc, 1.0, v68, 1.0
	v_mul_f32_e32 v73, v72, v71
	v_fma_f32 v74, -v70, v73, v72
	v_fmac_f32_e32 v73, v74, v71
	v_fma_f32 v70, -v70, v73, v72
	v_div_fmas_f32 v70, v70, v71, v73
	v_div_fixup_f32 v68, v70, v68, 1.0
	v_pk_fma_f32 v[132:133], v[46:47], v[68:69], v[132:133]
	s_waitcnt vmcnt(30)
	v_cvt_f32_f16_e32 v68, v222
	v_cvt_f32_f16_e32 v69, v223
	v_add_u32_e32 v96, 0xd2400, v94
	global_load_ushort v222, v96, s[40:41] offset:64
	v_add_u32_e32 v96, 0xd5e00, v94
	global_load_ushort v223, v96, s[40:41] offset:64
	v_mul_f32_e32 v68, 0xbfb8aa3b, v68
	v_mul_f32_e32 v69, 0xbfb8aa3b, v69
	v_exp_f32_e32 v68, v68
	v_exp_f32_e32 v69, v69
	s_nop 0
	v_pk_add_f32 v[68:69], v[68:69], 1.0 op_sel_hi:[1,0]
	s_nop 0
	v_div_scale_f32 v70, s[2:3], v69, v69, 1.0
	v_rcp_f32_e32 v71, v70
	s_nop 0
	v_fma_f32 v72, -v70, v71, 1.0
	v_fmac_f32_e32 v71, v72, v71
	v_div_scale_f32 v72, vcc, 1.0, v69, 1.0
	v_mul_f32_e32 v73, v72, v71
	v_fma_f32 v74, -v70, v73, v72
	v_fmac_f32_e32 v73, v74, v71
	v_fma_f32 v70, -v70, v73, v72
	v_div_fmas_f32 v70, v70, v71, v73
	v_div_fixup_f32 v69, v70, v69, 1.0
	v_div_scale_f32 v70, s[2:3], v68, v68, 1.0
	v_rcp_f32_e32 v71, v70
	s_nop 0
	v_fma_f32 v72, -v70, v71, 1.0
	v_fmac_f32_e32 v71, v72, v71
	v_div_scale_f32 v72, vcc, 1.0, v68, 1.0
	v_mul_f32_e32 v73, v72, v71
	v_fma_f32 v74, -v70, v73, v72
	v_fmac_f32_e32 v73, v74, v71
	v_fma_f32 v70, -v70, v73, v72
	v_div_fmas_f32 v70, v70, v71, v73
	v_div_fixup_f32 v68, v70, v68, 1.0
	v_pk_fma_f32 v[130:131], v[48:49], v[68:69], v[130:131]
	s_waitcnt vmcnt(30)
	v_cvt_f32_f16_e32 v68, v192
	v_cvt_f32_f16_e32 v69, v193
	v_mul_f32_e32 v68, 0xbfb8aa3b, v68
	v_mul_f32_e32 v69, 0xbfb8aa3b, v69
	v_exp_f32_e32 v68, v68
	v_exp_f32_e32 v69, v69
	s_nop 0
	v_pk_add_f32 v[68:69], v[68:69], 1.0 op_sel_hi:[1,0]
	s_nop 0
	v_div_scale_f32 v70, s[2:3], v69, v69, 1.0
	v_rcp_f32_e32 v71, v70
	s_nop 0
	v_fma_f32 v72, -v70, v71, 1.0
	v_fmac_f32_e32 v71, v72, v71
	v_div_scale_f32 v72, vcc, 1.0, v69, 1.0
	v_mul_f32_e32 v73, v72, v71
	v_fma_f32 v74, -v70, v73, v72
	v_fmac_f32_e32 v73, v74, v71
	v_fma_f32 v70, -v70, v73, v72
	v_div_fmas_f32 v70, v70, v71, v73
	v_div_fixup_f32 v69, v70, v69, 1.0
	v_div_scale_f32 v70, s[2:3], v68, v68, 1.0
	v_rcp_f32_e32 v71, v70
	s_nop 0
	v_fma_f32 v72, -v70, v71, 1.0
	v_fmac_f32_e32 v71, v72, v71
	v_div_scale_f32 v72, vcc, 1.0, v68, 1.0
	v_mul_f32_e32 v73, v72, v71
	v_fma_f32 v74, -v70, v73, v72
	v_fmac_f32_e32 v73, v74, v71
	v_fma_f32 v70, -v70, v73, v72
	v_div_fmas_f32 v70, v70, v71, v73
	v_div_fixup_f32 v68, v70, v68, 1.0
	v_pk_fma_f32 v[128:129], v[18:19], v[68:69], v[128:129]
	s_waitcnt vmcnt(28)
; __device__ __forceinline__ float sigmoidf_(float x) { return 1.f / (1.f + __expf(-x)); }
; __device__ __forceinline__ void phase_merge(const KP& p, char* smem, int* q, int xcc) {
;     ...
;           [&](int mi, int ni, int r, int row, int col, float v) {
;             const float gz = (float)G[(size_t)row * NU + col];
;             tot[mi][ni][r] += sigmoidf_(gz) * v;
;           },
	v_cvt_f32_f16_e32 v68, v194
	v_cvt_f32_f16_e32 v69, v195
	v_mul_f32_e32 v68, 0xbfb8aa3b, v68
	v_mul_f32_e32 v69, 0xbfb8aa3b, v69
	v_exp_f32_e32 v68, v68
	v_exp_f32_e32 v69, v69
	s_nop 0
	v_pk_add_f32 v[68:69], v[68:69], 1.0 op_sel_hi:[1,0]
	s_nop 0
	v_div_scale_f32 v70, s[2:3], v69, v69, 1.0
	v_rcp_f32_e32 v71, v70
	s_nop 0
	v_fma_f32 v72, -v70, v71, 1.0
	v_fmac_f32_e32 v71, v72, v71
	v_div_scale_f32 v72, vcc, 1.0, v69, 1.0
	v_mul_f32_e32 v73, v72, v71
	v_fma_f32 v74, -v70, v73, v72
	v_fmac_f32_e32 v73, v74, v71
	v_fma_f32 v70, -v70, v73, v72
	v_div_fmas_f32 v70, v70, v71, v73
	v_div_fixup_f32 v69, v70, v69, 1.0
	v_div_scale_f32 v70, s[2:3], v68, v68, 1.0
	v_rcp_f32_e32 v71, v70
	s_nop 0
	v_fma_f32 v72, -v70, v71, 1.0
	v_fmac_f32_e32 v71, v72, v71
	v_div_scale_f32 v72, vcc, 1.0, v68, 1.0
	v_mul_f32_e32 v73, v72, v71
	v_fma_f32 v74, -v70, v73, v72
	v_fmac_f32_e32 v73, v74, v71
	v_fma_f32 v70, -v70, v73, v72
	v_div_fmas_f32 v70, v70, v71, v73
	v_div_fixup_f32 v68, v70, v68, 1.0
	v_pk_fma_f32 v[126:127], v[20:21], v[68:69], v[126:127]
	s_waitcnt vmcnt(26)
	v_cvt_f32_f16_e32 v68, v196
	v_cvt_f32_f16_e32 v69, v197
	v_mul_f32_e32 v68, 0xbfb8aa3b, v68
	v_mul_f32_e32 v69, 0xbfb8aa3b, v69
	v_exp_f32_e32 v68, v68
	v_exp_f32_e32 v69, v69
	s_nop 0
	v_pk_add_f32 v[68:69], v[68:69], 1.0 op_sel_hi:[1,0]
	s_nop 0
	v_div_scale_f32 v70, s[2:3], v69, v69, 1.0
	v_rcp_f32_e32 v71, v70
	s_nop 0
	v_fma_f32 v72, -v70, v71, 1.0
	v_fmac_f32_e32 v71, v72, v71
	v_div_scale_f32 v72, vcc, 1.0, v69, 1.0
	v_mul_f32_e32 v73, v72, v71
	v_fma_f32 v74, -v70, v73, v72
	v_fmac_f32_e32 v73, v74, v71
	v_fma_f32 v70, -v70, v73, v72
	v_div_fmas_f32 v70, v70, v71, v73
	v_div_fixup_f32 v69, v70, v69, 1.0
	v_div_scale_f32 v70, s[2:3], v68, v68, 1.0
	v_rcp_f32_e32 v71, v70
	s_nop 0
	v_fma_f32 v72, -v70, v71, 1.0
	v_fmac_f32_e32 v71, v72, v71
	v_div_scale_f32 v72, vcc, 1.0, v68, 1.0
	v_mul_f32_e32 v73, v72, v71
	v_fma_f32 v74, -v70, v73, v72
	v_fmac_f32_e32 v73, v74, v71
	v_fma_f32 v70, -v70, v73, v72
	v_div_fmas_f32 v70, v70, v71, v73
	v_div_fixup_f32 v68, v70, v68, 1.0
	v_pk_fma_f32 v[124:125], v[22:23], v[68:69], v[124:125]
	s_waitcnt vmcnt(24)
	v_cvt_f32_f16_e32 v68, v198
	v_cvt_f32_f16_e32 v69, v199
	v_mul_f32_e32 v68, 0xbfb8aa3b, v68
	v_mul_f32_e32 v69, 0xbfb8aa3b, v69
	v_exp_f32_e32 v68, v68
	v_exp_f32_e32 v69, v69
	s_nop 0
	v_pk_add_f32 v[68:69], v[68:69], 1.0 op_sel_hi:[1,0]
	s_nop 0
	v_div_scale_f32 v70, s[2:3], v69, v69, 1.0
	v_rcp_f32_e32 v71, v70
	s_nop 0
	v_fma_f32 v72, -v70, v71, 1.0
	v_fmac_f32_e32 v71, v72, v71
	v_div_scale_f32 v72, vcc, 1.0, v69, 1.0
	v_mul_f32_e32 v73, v72, v71
	v_fma_f32 v74, -v70, v73, v72
	v_fmac_f32_e32 v73, v74, v71
	v_fma_f32 v70, -v70, v73, v72
	v_div_fmas_f32 v70, v70, v71, v73
	v_div_fixup_f32 v69, v70, v69, 1.0
	v_div_scale_f32 v70, s[2:3], v68, v68, 1.0
	v_rcp_f32_e32 v71, v70
	s_nop 0
	v_fma_f32 v72, -v70, v71, 1.0
	v_fmac_f32_e32 v71, v72, v71
	v_div_scale_f32 v72, vcc, 1.0, v68, 1.0
	v_mul_f32_e32 v73, v72, v71
	v_fma_f32 v74, -v70, v73, v72
	v_fmac_f32_e32 v73, v74, v71
	v_fma_f32 v70, -v70, v73, v72
	v_div_fmas_f32 v70, v70, v71, v73
	v_div_fixup_f32 v68, v70, v68, 1.0
	v_pk_fma_f32 v[122:123], v[24:25], v[68:69], v[122:123]
	s_waitcnt vmcnt(22)
	v_cvt_f32_f16_e32 v68, v200
	v_cvt_f32_f16_e32 v69, v201
	v_mul_f32_e32 v68, 0xbfb8aa3b, v68
	v_mul_f32_e32 v69, 0xbfb8aa3b, v69
	v_exp_f32_e32 v68, v68
	v_exp_f32_e32 v69, v69
	s_nop 0
	v_pk_add_f32 v[68:69], v[68:69], 1.0 op_sel_hi:[1,0]
	s_nop 0
	v_div_scale_f32 v70, s[2:3], v69, v69, 1.0
	v_rcp_f32_e32 v71, v70
	s_nop 0
	v_fma_f32 v72, -v70, v71, 1.0
	v_fmac_f32_e32 v71, v72, v71
	v_div_scale_f32 v72, vcc, 1.0, v69, 1.0
	v_mul_f32_e32 v73, v72, v71
	v_fma_f32 v74, -v70, v73, v72
	v_fmac_f32_e32 v73, v74, v71
	v_fma_f32 v70, -v70, v73, v72
	v_div_fmas_f32 v70, v70, v71, v73
	v_div_fixup_f32 v69, v70, v69, 1.0
	v_div_scale_f32 v70, s[2:3], v68, v68, 1.0
	v_rcp_f32_e32 v71, v70
	s_nop 0
	v_fma_f32 v72, -v70, v71, 1.0
	v_fmac_f32_e32 v71, v72, v71
	v_div_scale_f32 v72, vcc, 1.0, v68, 1.0
	v_mul_f32_e32 v73, v72, v71
	v_fma_f32 v74, -v70, v73, v72
	v_fmac_f32_e32 v73, v74, v71
	v_fma_f32 v70, -v70, v73, v72
	v_div_fmas_f32 v70, v70, v71, v73
	v_div_fixup_f32 v68, v70, v68, 1.0
	v_pk_fma_f32 v[120:121], v[26:27], v[68:69], v[120:121]
	s_waitcnt vmcnt(20)
	v_cvt_f32_f16_e32 v68, v202
	v_cvt_f32_f16_e32 v69, v203
	v_mul_f32_e32 v68, 0xbfb8aa3b, v68
	v_mul_f32_e32 v69, 0xbfb8aa3b, v69
	v_exp_f32_e32 v68, v68
	v_exp_f32_e32 v69, v69
	s_nop 0
	v_pk_add_f32 v[68:69], v[68:69], 1.0 op_sel_hi:[1,0]
	s_nop 0
	v_div_scale_f32 v70, s[2:3], v69, v69, 1.0
	v_rcp_f32_e32 v71, v70
	s_nop 0
	v_fma_f32 v72, -v70, v71, 1.0
	v_fmac_f32_e32 v71, v72, v71
	v_div_scale_f32 v72, vcc, 1.0, v69, 1.0
	v_mul_f32_e32 v73, v72, v71
	v_fma_f32 v74, -v70, v73, v72
	v_fmac_f32_e32 v73, v74, v71
	v_fma_f32 v70, -v70, v73, v72
	v_div_fmas_f32 v70, v70, v71, v73
	v_div_fixup_f32 v69, v70, v69, 1.0
	v_div_scale_f32 v70, s[2:3], v68, v68, 1.0
	v_rcp_f32_e32 v71, v70
	s_nop 0
	v_fma_f32 v72, -v70, v71, 1.0
	v_fmac_f32_e32 v71, v72, v71
	v_div_scale_f32 v72, vcc, 1.0, v68, 1.0
	v_mul_f32_e32 v73, v72, v71
	v_fma_f32 v74, -v70, v73, v72
	v_fmac_f32_e32 v73, v74, v71
	v_fma_f32 v70, -v70, v73, v72
	v_div_fmas_f32 v70, v70, v71, v73
	v_div_fixup_f32 v68, v70, v68, 1.0
	v_pk_fma_f32 v[118:119], v[28:29], v[68:69], v[118:119]
	s_waitcnt vmcnt(18)
; __device__ __forceinline__ float sigmoidf_(float x) { return 1.f / (1.f + __expf(-x)); }
; __device__ __forceinline__ void phase_merge(const KP& p, char* smem, int* q, int xcc) {
;     ...
;           [&](int mi, int ni, int r, int row, int col, float v) {
;             const float gz = (float)G[(size_t)row * NU + col];
;             tot[mi][ni][r] += sigmoidf_(gz) * v;
;           },
	v_cvt_f32_f16_e32 v68, v204
	v_cvt_f32_f16_e32 v69, v205
	v_mul_f32_e32 v68, 0xbfb8aa3b, v68
	v_mul_f32_e32 v69, 0xbfb8aa3b, v69
	v_exp_f32_e32 v68, v68
	v_exp_f32_e32 v69, v69
	s_nop 0
	v_pk_add_f32 v[68:69], v[68:69], 1.0 op_sel_hi:[1,0]
	s_nop 0
	v_div_scale_f32 v70, s[2:3], v69, v69, 1.0
	v_rcp_f32_e32 v71, v70
	s_nop 0
	v_fma_f32 v72, -v70, v71, 1.0
	v_fmac_f32_e32 v71, v72, v71
	v_div_scale_f32 v72, vcc, 1.0, v69, 1.0
	v_mul_f32_e32 v73, v72, v71
	v_fma_f32 v74, -v70, v73, v72
	v_fmac_f32_e32 v73, v74, v71
	v_fma_f32 v70, -v70, v73, v72
	v_div_fmas_f32 v70, v70, v71, v73
	v_div_fixup_f32 v69, v70, v69, 1.0
	v_div_scale_f32 v70, s[2:3], v68, v68, 1.0
	v_rcp_f32_e32 v71, v70
	s_nop 0
	v_fma_f32 v72, -v70, v71, 1.0
	v_fmac_f32_e32 v71, v72, v71
	v_div_scale_f32 v72, vcc, 1.0, v68, 1.0
	v_mul_f32_e32 v73, v72, v71
	v_fma_f32 v74, -v70, v73, v72
	v_fmac_f32_e32 v73, v74, v71
	v_fma_f32 v70, -v70, v73, v72
	v_div_fmas_f32 v70, v70, v71, v73
	v_div_fixup_f32 v68, v70, v68, 1.0
	v_pk_fma_f32 v[116:117], v[30:31], v[68:69], v[116:117]
	s_waitcnt vmcnt(16)
	v_cvt_f32_f16_e32 v68, v206
	v_cvt_f32_f16_e32 v69, v207
	v_mul_f32_e32 v68, 0xbfb8aa3b, v68
	v_mul_f32_e32 v69, 0xbfb8aa3b, v69
	v_exp_f32_e32 v68, v68
	v_exp_f32_e32 v69, v69
	s_nop 0
	v_pk_add_f32 v[68:69], v[68:69], 1.0 op_sel_hi:[1,0]
	s_nop 0
	v_div_scale_f32 v70, s[2:3], v69, v69, 1.0
	v_rcp_f32_e32 v71, v70
	s_nop 0
	v_fma_f32 v72, -v70, v71, 1.0
	v_fmac_f32_e32 v71, v72, v71
	v_div_scale_f32 v72, vcc, 1.0, v69, 1.0
	v_mul_f32_e32 v73, v72, v71
	v_fma_f32 v74, -v70, v73, v72
	v_fmac_f32_e32 v73, v74, v71
	v_fma_f32 v70, -v70, v73, v72
	v_div_fmas_f32 v70, v70, v71, v73
	v_div_fixup_f32 v69, v70, v69, 1.0
	v_div_scale_f32 v70, s[2:3], v68, v68, 1.0
	v_rcp_f32_e32 v71, v70
	s_nop 0
	v_fma_f32 v72, -v70, v71, 1.0
	v_fmac_f32_e32 v71, v72, v71
	v_div_scale_f32 v72, vcc, 1.0, v68, 1.0
	v_mul_f32_e32 v73, v72, v71
	v_fma_f32 v74, -v70, v73, v72
	v_fmac_f32_e32 v73, v74, v71
	v_fma_f32 v70, -v70, v73, v72
	v_div_fmas_f32 v70, v70, v71, v73
	v_div_fixup_f32 v68, v70, v68, 1.0
	v_pk_fma_f32 v[114:115], v[32:33], v[68:69], v[114:115]
	s_waitcnt vmcnt(14)
	v_cvt_f32_f16_e32 v68, v208
	v_cvt_f32_f16_e32 v69, v209
	v_mul_f32_e32 v68, 0xbfb8aa3b, v68
	v_mul_f32_e32 v69, 0xbfb8aa3b, v69
	v_exp_f32_e32 v68, v68
	v_exp_f32_e32 v69, v69
	s_nop 0
	v_pk_add_f32 v[68:69], v[68:69], 1.0 op_sel_hi:[1,0]
	s_nop 0
	v_div_scale_f32 v70, s[2:3], v69, v69, 1.0
	v_rcp_f32_e32 v71, v70
	s_nop 0
	v_fma_f32 v72, -v70, v71, 1.0
	v_fmac_f32_e32 v71, v72, v71
	v_div_scale_f32 v72, vcc, 1.0, v69, 1.0
	v_mul_f32_e32 v73, v72, v71
	v_fma_f32 v74, -v70, v73, v72
	v_fmac_f32_e32 v73, v74, v71
	v_fma_f32 v70, -v70, v73, v72
	v_div_fmas_f32 v70, v70, v71, v73
	v_div_fixup_f32 v69, v70, v69, 1.0
	v_div_scale_f32 v70, s[2:3], v68, v68, 1.0
	v_rcp_f32_e32 v71, v70
	s_nop 0
	v_fma_f32 v72, -v70, v71, 1.0
	v_fmac_f32_e32 v71, v72, v71
	v_div_scale_f32 v72, vcc, 1.0, v68, 1.0
	v_mul_f32_e32 v73, v72, v71
	v_fma_f32 v74, -v70, v73, v72
	v_fmac_f32_e32 v73, v74, v71
	v_fma_f32 v70, -v70, v73, v72
	v_div_fmas_f32 v70, v70, v71, v73
	v_div_fixup_f32 v68, v70, v68, 1.0
	v_pk_fma_f32 v[112:113], v[2:3], v[68:69], v[112:113]
	s_waitcnt vmcnt(12)
	v_cvt_f32_f16_e32 v68, v210
	v_cvt_f32_f16_e32 v69, v211
	v_mul_f32_e32 v68, 0xbfb8aa3b, v68
	v_mul_f32_e32 v69, 0xbfb8aa3b, v69
	v_exp_f32_e32 v68, v68
	v_exp_f32_e32 v69, v69
	s_nop 0
	v_pk_add_f32 v[68:69], v[68:69], 1.0 op_sel_hi:[1,0]
	s_nop 0
	v_div_scale_f32 v70, s[2:3], v69, v69, 1.0
	v_rcp_f32_e32 v71, v70
	s_nop 0
	v_fma_f32 v72, -v70, v71, 1.0
	v_fmac_f32_e32 v71, v72, v71
	v_div_scale_f32 v72, vcc, 1.0, v69, 1.0
	v_mul_f32_e32 v73, v72, v71
	v_fma_f32 v74, -v70, v73, v72
	v_fmac_f32_e32 v73, v74, v71
	v_fma_f32 v70, -v70, v73, v72
	v_div_fmas_f32 v70, v70, v71, v73
	v_div_fixup_f32 v69, v70, v69, 1.0
	v_div_scale_f32 v70, s[2:3], v68, v68, 1.0
	v_rcp_f32_e32 v71, v70
	s_nop 0
	v_fma_f32 v72, -v70, v71, 1.0
	v_fmac_f32_e32 v71, v72, v71
	v_div_scale_f32 v72, vcc, 1.0, v68, 1.0
	v_mul_f32_e32 v73, v72, v71
	v_fma_f32 v74, -v70, v73, v72
	v_fmac_f32_e32 v73, v74, v71
	v_fma_f32 v70, -v70, v73, v72
	v_div_fmas_f32 v70, v70, v71, v73
	v_div_fixup_f32 v68, v70, v68, 1.0
	v_pk_fma_f32 v[110:111], v[4:5], v[68:69], v[110:111]
	s_waitcnt vmcnt(10)
	v_cvt_f32_f16_e32 v68, v212
	v_cvt_f32_f16_e32 v69, v213
	v_mul_f32_e32 v68, 0xbfb8aa3b, v68
	v_mul_f32_e32 v69, 0xbfb8aa3b, v69
	v_exp_f32_e32 v68, v68
	v_exp_f32_e32 v69, v69
	s_nop 0
	v_pk_add_f32 v[68:69], v[68:69], 1.0 op_sel_hi:[1,0]
	s_nop 0
	v_div_scale_f32 v70, s[2:3], v69, v69, 1.0
	v_rcp_f32_e32 v71, v70
	s_nop 0
	v_fma_f32 v72, -v70, v71, 1.0
	v_fmac_f32_e32 v71, v72, v71
	v_div_scale_f32 v72, vcc, 1.0, v69, 1.0
	v_mul_f32_e32 v73, v72, v71
	v_fma_f32 v74, -v70, v73, v72
	v_fmac_f32_e32 v73, v74, v71
	v_fma_f32 v70, -v70, v73, v72
	v_div_fmas_f32 v70, v70, v71, v73
	v_div_fixup_f32 v69, v70, v69, 1.0
	v_div_scale_f32 v70, s[2:3], v68, v68, 1.0
	v_rcp_f32_e32 v71, v70
	s_nop 0
	v_fma_f32 v72, -v70, v71, 1.0
	v_fmac_f32_e32 v71, v72, v71
	v_div_scale_f32 v72, vcc, 1.0, v68, 1.0
	v_mul_f32_e32 v73, v72, v71
	v_fma_f32 v74, -v70, v73, v72
	v_fmac_f32_e32 v73, v74, v71
	v_fma_f32 v70, -v70, v73, v72
	v_div_fmas_f32 v70, v70, v71, v73
	v_div_fixup_f32 v68, v70, v68, 1.0
	v_pk_fma_f32 v[108:109], v[6:7], v[68:69], v[108:109]
	s_waitcnt vmcnt(8)
;   __device__ __forceinline__ half_t* u() const { return (half_t*)(ws() + OFF_u); }
;   __device__ __forceinline__ half_t* wpT() const { return (half_t*)(ws() + OFF_wpT); }
;   __device__ __forceinline__ half_t* ya() const { return (half_t*)(ws() + OFF_ya); }
;   __device__ __forceinline__ half_t* yb() const { return (half_t*)(ws() + OFF_yb); }
;   __device__ __forceinline__ half_t* yc() const { return (half_t*)(ws() + OFF_yc); }
; __device__ __forceinline__ float sigmoidf_(float x) { return 1.f / (1.f + __expf(-x)); }
; __device__ __forceinline__ void phase_merge(const KP& p, char* smem, int* q, int xcc) {
;     ...
;     for (int br = 0; br < 3; ++br) {
;       const half_t* A = (br == 0 ? p.ya() : (br == 1 ? p.yb() : p.yc())) + (size_t)m0 * 512;
;       const half_t* B = p.wpT() + (size_t)br * DM * 512 + (size_t)n0 * 512;
;       const half_t* G = p.u() + (size_t)m0 * NU + C_GM + br * 1024 + n0;
;       gemm_tile<2>(
;           512, [&](int r, int k) { return *(const uint4*)(A + (size_t)r * 512 + k); },
;           [&](int r, int k) { return *(const uint4*)(B + (size_t)r * 512 + k); },
;           [&](int mi, int ni, int r, int row, int col, float v) {
;             const float gz = (float)G[(size_t)row * NU + col];
;             tot[mi][ni][r] += sigmoidf_(gz) * v;
;           },
	v_cvt_f32_f16_e32 v68, v214
	v_cvt_f32_f16_e32 v69, v215
	v_mul_f32_e32 v68, 0xbfb8aa3b, v68
	v_mul_f32_e32 v69, 0xbfb8aa3b, v69
	v_exp_f32_e32 v68, v68
	v_exp_f32_e32 v69, v69
	s_nop 0
	v_pk_add_f32 v[68:69], v[68:69], 1.0 op_sel_hi:[1,0]
	s_nop 0
	v_div_scale_f32 v70, s[2:3], v69, v69, 1.0
	v_rcp_f32_e32 v71, v70
	s_nop 0
	v_fma_f32 v72, -v70, v71, 1.0
	v_fmac_f32_e32 v71, v72, v71
	v_div_scale_f32 v72, vcc, 1.0, v69, 1.0
	v_mul_f32_e32 v73, v72, v71
	v_fma_f32 v74, -v70, v73, v72
	v_fmac_f32_e32 v73, v74, v71
	v_fma_f32 v70, -v70, v73, v72
	v_div_fmas_f32 v70, v70, v71, v73
	v_div_fixup_f32 v69, v70, v69, 1.0
	v_div_scale_f32 v70, s[2:3], v68, v68, 1.0
	v_rcp_f32_e32 v71, v70
	s_nop 0
	v_fma_f32 v72, -v70, v71, 1.0
	v_fmac_f32_e32 v71, v72, v71
	v_div_scale_f32 v72, vcc, 1.0, v68, 1.0
	v_mul_f32_e32 v73, v72, v71
	v_fma_f32 v74, -v70, v73, v72
	v_fmac_f32_e32 v73, v74, v71
	v_fma_f32 v70, -v70, v73, v72
	v_div_fmas_f32 v70, v70, v71, v73
	v_div_fixup_f32 v68, v70, v68, 1.0
	v_pk_fma_f32 v[106:107], v[8:9], v[68:69], v[106:107]
	s_waitcnt vmcnt(6)
	v_cvt_f32_f16_e32 v68, v216
	v_cvt_f32_f16_e32 v69, v217
	v_mul_f32_e32 v68, 0xbfb8aa3b, v68
	v_mul_f32_e32 v69, 0xbfb8aa3b, v69
	v_exp_f32_e32 v68, v68
	v_exp_f32_e32 v69, v69
	s_nop 0
	v_pk_add_f32 v[68:69], v[68:69], 1.0 op_sel_hi:[1,0]
	s_nop 0
	v_div_scale_f32 v70, s[2:3], v69, v69, 1.0
	v_rcp_f32_e32 v71, v70
	s_nop 0
	v_fma_f32 v72, -v70, v71, 1.0
	v_fmac_f32_e32 v71, v72, v71
	v_div_scale_f32 v72, vcc, 1.0, v69, 1.0
	v_mul_f32_e32 v73, v72, v71
	v_fma_f32 v74, -v70, v73, v72
	v_fmac_f32_e32 v73, v74, v71
	v_fma_f32 v70, -v70, v73, v72
	v_div_fmas_f32 v70, v70, v71, v73
	v_div_fixup_f32 v69, v70, v69, 1.0
	v_div_scale_f32 v70, s[2:3], v68, v68, 1.0
	v_rcp_f32_e32 v71, v70
	s_nop 0
	v_fma_f32 v72, -v70, v71, 1.0
	v_fmac_f32_e32 v71, v72, v71
	v_div_scale_f32 v72, vcc, 1.0, v68, 1.0
	v_mul_f32_e32 v73, v72, v71
	v_fma_f32 v74, -v70, v73, v72
	v_fmac_f32_e32 v73, v74, v71
	v_fma_f32 v70, -v70, v73, v72
	v_div_fmas_f32 v70, v70, v71, v73
	v_div_fixup_f32 v68, v70, v68, 1.0
	v_pk_fma_f32 v[104:105], v[10:11], v[68:69], v[104:105]
	s_waitcnt vmcnt(4)
	v_cvt_f32_f16_e32 v68, v218
	v_cvt_f32_f16_e32 v69, v219
	v_mul_f32_e32 v68, 0xbfb8aa3b, v68
	v_mul_f32_e32 v69, 0xbfb8aa3b, v69
	v_exp_f32_e32 v68, v68
	v_exp_f32_e32 v69, v69
	s_nop 0
	v_pk_add_f32 v[68:69], v[68:69], 1.0 op_sel_hi:[1,0]
	s_nop 0
	v_div_scale_f32 v70, s[2:3], v69, v69, 1.0
	v_rcp_f32_e32 v71, v70
	s_nop 0
	v_fma_f32 v72, -v70, v71, 1.0
	v_fmac_f32_e32 v71, v72, v71
	v_div_scale_f32 v72, vcc, 1.0, v69, 1.0
	v_mul_f32_e32 v73, v72, v71
	v_fma_f32 v74, -v70, v73, v72
	v_fmac_f32_e32 v73, v74, v71
	v_fma_f32 v70, -v70, v73, v72
	v_div_fmas_f32 v70, v70, v71, v73
	v_div_fixup_f32 v69, v70, v69, 1.0
	v_div_scale_f32 v70, s[2:3], v68, v68, 1.0
	v_rcp_f32_e32 v71, v70
	s_nop 0
	v_fma_f32 v72, -v70, v71, 1.0
	v_fmac_f32_e32 v71, v72, v71
	v_div_scale_f32 v72, vcc, 1.0, v68, 1.0
	v_mul_f32_e32 v73, v72, v71
	v_fma_f32 v74, -v70, v73, v72
	v_fmac_f32_e32 v73, v74, v71
	v_fma_f32 v70, -v70, v73, v72
	v_div_fmas_f32 v70, v70, v71, v73
	v_div_fixup_f32 v68, v70, v68, 1.0
	v_pk_fma_f32 v[102:103], v[12:13], v[68:69], v[102:103]
	s_waitcnt vmcnt(2)
	v_cvt_f32_f16_e32 v68, v220
	v_cvt_f32_f16_e32 v69, v221
	v_mul_f32_e32 v68, 0xbfb8aa3b, v68
	v_mul_f32_e32 v69, 0xbfb8aa3b, v69
	v_exp_f32_e32 v68, v68
	v_exp_f32_e32 v69, v69
	s_nop 0
	v_pk_add_f32 v[68:69], v[68:69], 1.0 op_sel_hi:[1,0]
	s_nop 0
	v_div_scale_f32 v70, s[2:3], v69, v69, 1.0
	v_rcp_f32_e32 v71, v70
	s_nop 0
	v_fma_f32 v72, -v70, v71, 1.0
	v_fmac_f32_e32 v71, v72, v71
	v_div_scale_f32 v72, vcc, 1.0, v69, 1.0
	v_mul_f32_e32 v73, v72, v71
	v_fma_f32 v74, -v70, v73, v72
	v_fmac_f32_e32 v73, v74, v71
	v_fma_f32 v70, -v70, v73, v72
	v_div_fmas_f32 v70, v70, v71, v73
	v_div_fixup_f32 v69, v70, v69, 1.0
	v_div_scale_f32 v70, s[2:3], v68, v68, 1.0
	v_rcp_f32_e32 v71, v70
	s_nop 0
	v_fma_f32 v72, -v70, v71, 1.0
	v_fmac_f32_e32 v71, v72, v71
	v_div_scale_f32 v72, vcc, 1.0, v68, 1.0
	v_mul_f32_e32 v73, v72, v71
	v_fma_f32 v74, -v70, v73, v72
	v_fmac_f32_e32 v73, v74, v71
	v_fma_f32 v70, -v70, v73, v72
	v_div_fmas_f32 v70, v70, v71, v73
	v_div_fixup_f32 v68, v70, v68, 1.0
	v_pk_fma_f32 v[100:101], v[14:15], v[68:69], v[100:101]
	s_waitcnt vmcnt(0)
	v_cvt_f32_f16_e32 v68, v222
	v_cvt_f32_f16_e32 v69, v223
	v_mul_f32_e32 v68, 0xbfb8aa3b, v68
	v_mul_f32_e32 v69, 0xbfb8aa3b, v69
	v_exp_f32_e32 v68, v68
	v_exp_f32_e32 v69, v69
	s_nop 0
	v_pk_add_f32 v[68:69], v[68:69], 1.0 op_sel_hi:[1,0]
	s_nop 0
	v_div_scale_f32 v70, s[2:3], v69, v69, 1.0
	v_rcp_f32_e32 v71, v70
	s_nop 0
	v_fma_f32 v72, -v70, v71, 1.0
	v_fmac_f32_e32 v71, v72, v71
	v_div_scale_f32 v72, vcc, 1.0, v69, 1.0
	v_mul_f32_e32 v73, v72, v71
	v_fma_f32 v74, -v70, v73, v72
	v_fmac_f32_e32 v73, v74, v71
	v_fma_f32 v70, -v70, v73, v72
	v_div_fmas_f32 v70, v70, v71, v73
	v_div_fixup_f32 v69, v70, v69, 1.0
	v_div_scale_f32 v70, s[2:3], v68, v68, 1.0
	v_rcp_f32_e32 v71, v70
	s_nop 0
	v_fma_f32 v72, -v70, v71, 1.0
	v_fmac_f32_e32 v71, v72, v71
	v_div_scale_f32 v72, vcc, 1.0, v68, 1.0
	v_mul_f32_e32 v73, v72, v71
	v_fma_f32 v74, -v70, v73, v72
	v_fmac_f32_e32 v73, v74, v71
	v_fma_f32 v70, -v70, v73, v72
	v_div_fmas_f32 v70, v70, v71, v73
	v_div_fixup_f32 v68, v70, v68, 1.0
	v_pk_fma_f32 v[98:99], v[16:17], v[68:69], v[98:99]
	s_cmp_lg_u32 s56, 3
	s_cbranch_scc1 .LBB0_1742
;   __device__ __forceinline__ const float* x() const { return (const float*)(const __attribute__((address_space(1))) float*)kp[0]; }
;   __device__ __forceinline__ half_t* mm() const { return (half_t*)(ws() + OFF_mm); }
; __device__ __forceinline__ void phase_merge(const KP& p, char* smem, int* q, int xcc) {
;     ...
;     int tidx = threadIdx.x;
;     asm volatile("" : "+v"(tidx));
;     const int lane = tidx & 63, wid = tidx >> 6, wm = wid >> 1, wn = wid & 1;
; #pragma unroll
;     for (int mi = 0; mi < 2; ++mi)
; #pragma unroll
;       for (int ni = 0; ni < 2; ++ni)
; #pragma unroll
;         for (int r = 0; r < 16; ++r) {
;           const int row = wm * 64 + mi * 32 + (r & 3) + 8 * (r >> 2) + 4 * (lane >> 5);
;           const int col = wn * 64 + ni * 32 + (lane & 31);
;           p.mm()[(size_t)(m0 + row) * DM + n0 + col] = (half_t)tot[mi][ni][r];
;         }
	v_mov_b32_e32 v0, v224
	s_add_u32 s2, s44, s18
	v_ashrrev_i32_e32 v2, 1, v0
	v_and_b32_e32 v2, 0xffffffc0, v2
	v_lshrrev_b32_e32 v3, 3, v0
	v_and_b32_e32 v0, 0x5f, v0
	v_add_u32_e32 v2, s14, v2
	s_addc_u32 s3, s45, s19
	v_lshlrev_b32_e32 v0, 1, v0
	v_and_or_b32 v2, v3, 4, v2
	v_lshl_add_u64 v[4:5], s[2:3], 0, v[0:1]
	v_cvt_f16_f32_e32 v0, v160
	v_ashrrev_i32_e32 v3, 31, v2
	v_lshlrev_b64 v[6:7], 11, v[2:3]
	v_lshl_add_u64 v[6:7], v[4:5], 0, v[6:7]
	global_store_short v[6:7], v0, off
	v_cvt_f16_f32_e32 v0, v161
	v_or_b32_e32 v8, 1, v2
	v_ashrrev_i32_e32 v9, 31, v8
	v_lshlrev_b64 v[8:9], 11, v[8:9]
	v_lshl_add_u64 v[8:9], v[4:5], 0, v[8:9]
	global_store_short v[8:9], v0, off
	v_cvt_f16_f32_e32 v0, v158
	v_or_b32_e32 v10, 2, v2
	v_ashrrev_i32_e32 v11, 31, v10
	v_lshlrev_b64 v[10:11], 11, v[10:11]
	v_lshl_add_u64 v[10:11], v[4:5], 0, v[10:11]
	global_store_short v[10:11], v0, off
	v_cvt_f16_f32_e32 v0, v159
	v_or_b32_e32 v12, 3, v2
	v_ashrrev_i32_e32 v13, 31, v12
	v_lshlrev_b64 v[12:13], 11, v[12:13]
	v_lshl_add_u64 v[12:13], v[4:5], 0, v[12:13]
	global_store_short v[12:13], v0, off
	v_cvt_f16_f32_e32 v0, v156
	v_or_b32_e32 v14, 8, v2
	v_ashrrev_i32_e32 v15, 31, v14
	v_lshlrev_b64 v[14:15], 11, v[14:15]
	v_lshl_add_u64 v[14:15], v[4:5], 0, v[14:15]
	global_store_short v[14:15], v0, off
	v_cvt_f16_f32_e32 v0, v157
	v_or_b32_e32 v16, 9, v2
	v_ashrrev_i32_e32 v17, 31, v16
	v_lshlrev_b64 v[16:17], 11, v[16:17]
	v_lshl_add_u64 v[16:17], v[4:5], 0, v[16:17]
	global_store_short v[16:17], v0, off
	v_cvt_f16_f32_e32 v0, v154
	v_or_b32_e32 v18, 10, v2
	v_ashrrev_i32_e32 v19, 31, v18
	v_lshlrev_b64 v[18:19], 11, v[18:19]
	v_lshl_add_u64 v[18:19], v[4:5], 0, v[18:19]
	global_store_short v[18:19], v0, off
	v_cvt_f16_f32_e32 v0, v155
	v_or_b32_e32 v20, 11, v2
	v_ashrrev_i32_e32 v21, 31, v20
	v_lshlrev_b64 v[20:21], 11, v[20:21]
	v_lshl_add_u64 v[20:21], v[4:5], 0, v[20:21]
	global_store_short v[20:21], v0, off
	v_cvt_f16_f32_e32 v0, v152
	v_or_b32_e32 v22, 16, v2
	v_ashrrev_i32_e32 v23, 31, v22
	v_lshlrev_b64 v[22:23], 11, v[22:23]
	v_lshl_add_u64 v[22:23], v[4:5], 0, v[22:23]
	global_store_short v[22:23], v0, off
	v_cvt_f16_f32_e32 v0, v153
	v_or_b32_e32 v24, 17, v2
	v_ashrrev_i32_e32 v25, 31, v24
	v_lshlrev_b64 v[24:25], 11, v[24:25]
	v_lshl_add_u64 v[24:25], v[4:5], 0, v[24:25]
	global_store_short v[24:25], v0, off
	v_cvt_f16_f32_e32 v0, v150
	v_or_b32_e32 v26, 18, v2
	v_ashrrev_i32_e32 v27, 31, v26
	v_lshlrev_b64 v[26:27], 11, v[26:27]
	v_lshl_add_u64 v[26:27], v[4:5], 0, v[26:27]
	global_store_short v[26:27], v0, off
	v_cvt_f16_f32_e32 v0, v151
	v_or_b32_e32 v28, 19, v2
	v_ashrrev_i32_e32 v29, 31, v28
	v_lshlrev_b64 v[28:29], 11, v[28:29]
	v_lshl_add_u64 v[28:29], v[4:5], 0, v[28:29]
	global_store_short v[28:29], v0, off
	v_cvt_f16_f32_e32 v0, v148
	v_or_b32_e32 v30, 24, v2
	v_ashrrev_i32_e32 v31, 31, v30
	v_lshlrev_b64 v[30:31], 11, v[30:31]
	v_lshl_add_u64 v[30:31], v[4:5], 0, v[30:31]
	global_store_short v[30:31], v0, off
	v_cvt_f16_f32_e32 v0, v149
	v_or_b32_e32 v32, 25, v2
	v_ashrrev_i32_e32 v33, 31, v32
	v_lshlrev_b64 v[32:33], 11, v[32:33]
	v_lshl_add_u64 v[32:33], v[4:5], 0, v[32:33]
	global_store_short v[32:33], v0, off
	v_cvt_f16_f32_e32 v0, v146
	v_or_b32_e32 v34, 26, v2
	v_ashrrev_i32_e32 v35, 31, v34
	v_lshlrev_b64 v[34:35], 11, v[34:35]
	v_lshl_add_u64 v[34:35], v[4:5], 0, v[34:35]
	global_store_short v[34:35], v0, off
	v_cvt_f16_f32_e32 v0, v147
	v_or_b32_e32 v36, 27, v2
	v_ashrrev_i32_e32 v37, 31, v36
	v_lshlrev_b64 v[36:37], 11, v[36:37]
	v_lshl_add_u64 v[36:37], v[4:5], 0, v[36:37]
	global_store_short v[36:37], v0, off
	v_cvt_f16_f32_e32 v0, v144
	v_cvt_f16_f32_e32 v3, v145
	v_cvt_f16_f32_e32 v38, v142
	v_cvt_f16_f32_e32 v39, v143
	global_store_short v[6:7], v0, off offset:64
	global_store_short v[8:9], v3, off offset:64
	global_store_short v[10:11], v38, off offset:64
	global_store_short v[12:13], v39, off offset:64
	v_cvt_f16_f32_e32 v0, v140
	v_cvt_f16_f32_e32 v3, v141
	v_cvt_f16_f32_e32 v6, v138
	v_cvt_f16_f32_e32 v7, v139
	global_store_short v[14:15], v0, off offset:64
	global_store_short v[16:17], v3, off offset:64
	global_store_short v[18:19], v6, off offset:64
	global_store_short v[20:21], v7, off offset:64
	v_cvt_f16_f32_e32 v0, v136
	v_cvt_f16_f32_e32 v3, v137
	v_cvt_f16_f32_e32 v6, v134
	v_cvt_f16_f32_e32 v7, v135
	global_store_short v[22:23], v0, off offset:64
	global_store_short v[24:25], v3, off offset:64
	global_store_short v[26:27], v6, off offset:64
	global_store_short v[28:29], v7, off offset:64
	v_cvt_f16_f32_e32 v0, v132
	v_cvt_f16_f32_e32 v3, v133
	v_cvt_f16_f32_e32 v6, v130
	v_cvt_f16_f32_e32 v7, v131
	global_store_short v[30:31], v0, off offset:64
;   __device__ __forceinline__ const float* x() const { return (const float*)(const __attribute__((address_space(1))) float*)kp[0]; }
;   __device__ __forceinline__ half_t* mm() const { return (half_t*)(ws() + OFF_mm); }
; __device__ __forceinline__ void phase_merge(const KP& p, char* smem, int* q, int xcc) {
;     ...
;     int tidx = threadIdx.x;
;     asm volatile("" : "+v"(tidx));
;     const int lane = tidx & 63, wid = tidx >> 6, wm = wid >> 1, wn = wid & 1;
; #pragma unroll
;     for (int mi = 0; mi < 2; ++mi)
; #pragma unroll
;       for (int ni = 0; ni < 2; ++ni)
; #pragma unroll
;         for (int r = 0; r < 16; ++r) {
;           const int row = wm * 64 + mi * 32 + (r & 3) + 8 * (r >> 2) + 4 * (lane >> 5);
;           const int col = wn * 64 + ni * 32 + (lane & 31);
;           p.mm()[(size_t)(m0 + row) * DM + n0 + col] = (half_t)tot[mi][ni][r];
;         }
	global_store_short v[32:33], v3, off offset:64
	global_store_short v[34:35], v6, off offset:64
	global_store_short v[36:37], v7, off offset:64
	v_or_b32_e32 v6, 32, v2
	v_cvt_f16_f32_e32 v0, v128
	v_ashrrev_i32_e32 v7, 31, v6
	v_lshlrev_b64 v[6:7], 11, v[6:7]
	v_lshl_add_u64 v[6:7], v[4:5], 0, v[6:7]
	global_store_short v[6:7], v0, off
	v_cvt_f16_f32_e32 v0, v129
	v_or_b32_e32 v8, 33, v2
	v_ashrrev_i32_e32 v9, 31, v8
	v_lshlrev_b64 v[8:9], 11, v[8:9]
	v_lshl_add_u64 v[8:9], v[4:5], 0, v[8:9]
	global_store_short v[8:9], v0, off
	v_cvt_f16_f32_e32 v0, v126
	v_or_b32_e32 v10, 34, v2
	v_ashrrev_i32_e32 v11, 31, v10
	v_lshlrev_b64 v[10:11], 11, v[10:11]
	v_lshl_add_u64 v[10:11], v[4:5], 0, v[10:11]
	global_store_short v[10:11], v0, off
	v_cvt_f16_f32_e32 v0, v127
	v_or_b32_e32 v12, 35, v2
	v_ashrrev_i32_e32 v13, 31, v12
	v_lshlrev_b64 v[12:13], 11, v[12:13]
	v_lshl_add_u64 v[12:13], v[4:5], 0, v[12:13]
	global_store_short v[12:13], v0, off
	v_cvt_f16_f32_e32 v0, v124
	v_or_b32_e32 v14, 40, v2
	v_ashrrev_i32_e32 v15, 31, v14
	v_lshlrev_b64 v[14:15], 11, v[14:15]
	v_lshl_add_u64 v[14:15], v[4:5], 0, v[14:15]
	global_store_short v[14:15], v0, off
	v_cvt_f16_f32_e32 v0, v125
	v_or_b32_e32 v16, 41, v2
	v_ashrrev_i32_e32 v17, 31, v16
	v_lshlrev_b64 v[16:17], 11, v[16:17]
	v_lshl_add_u64 v[16:17], v[4:5], 0, v[16:17]
	global_store_short v[16:17], v0, off
	v_cvt_f16_f32_e32 v0, v122
	v_or_b32_e32 v18, 42, v2
	v_ashrrev_i32_e32 v19, 31, v18
	v_lshlrev_b64 v[18:19], 11, v[18:19]
	v_lshl_add_u64 v[18:19], v[4:5], 0, v[18:19]
	global_store_short v[18:19], v0, off
	v_cvt_f16_f32_e32 v0, v123
	v_or_b32_e32 v20, 43, v2
	v_ashrrev_i32_e32 v21, 31, v20
	v_lshlrev_b64 v[20:21], 11, v[20:21]
	v_lshl_add_u64 v[20:21], v[4:5], 0, v[20:21]
	global_store_short v[20:21], v0, off
	v_cvt_f16_f32_e32 v0, v120
	v_or_b32_e32 v22, 48, v2
	v_ashrrev_i32_e32 v23, 31, v22
	v_lshlrev_b64 v[22:23], 11, v[22:23]
	v_lshl_add_u64 v[22:23], v[4:5], 0, v[22:23]
	global_store_short v[22:23], v0, off
	v_cvt_f16_f32_e32 v0, v121
	v_or_b32_e32 v24, 49, v2
	v_ashrrev_i32_e32 v25, 31, v24
	v_lshlrev_b64 v[24:25], 11, v[24:25]
	v_lshl_add_u64 v[24:25], v[4:5], 0, v[24:25]
	global_store_short v[24:25], v0, off
	v_cvt_f16_f32_e32 v0, v118
	v_or_b32_e32 v26, 50, v2
	v_ashrrev_i32_e32 v27, 31, v26
	v_lshlrev_b64 v[26:27], 11, v[26:27]
	v_lshl_add_u64 v[26:27], v[4:5], 0, v[26:27]
	global_store_short v[26:27], v0, off
	v_cvt_f16_f32_e32 v0, v119
	v_or_b32_e32 v28, 51, v2
	v_ashrrev_i32_e32 v29, 31, v28
	v_lshlrev_b64 v[28:29], 11, v[28:29]
	v_lshl_add_u64 v[28:29], v[4:5], 0, v[28:29]
	global_store_short v[28:29], v0, off
	v_cvt_f16_f32_e32 v0, v116
	v_or_b32_e32 v30, 56, v2
	v_ashrrev_i32_e32 v31, 31, v30
	v_lshlrev_b64 v[30:31], 11, v[30:31]
	v_lshl_add_u64 v[30:31], v[4:5], 0, v[30:31]
	global_store_short v[30:31], v0, off
	v_cvt_f16_f32_e32 v0, v117
	v_or_b32_e32 v32, 57, v2
	v_ashrrev_i32_e32 v33, 31, v32
	v_lshlrev_b64 v[32:33], 11, v[32:33]
	v_lshl_add_u64 v[32:33], v[4:5], 0, v[32:33]
	global_store_short v[32:33], v0, off
	v_cvt_f16_f32_e32 v0, v114
	v_or_b32_e32 v34, 58, v2
	v_ashrrev_i32_e32 v35, 31, v34
	v_lshlrev_b64 v[34:35], 11, v[34:35]
	v_lshl_add_u64 v[34:35], v[4:5], 0, v[34:35]
	global_store_short v[34:35], v0, off
	v_cvt_f16_f32_e32 v0, v115
	v_or_b32_e32 v2, 59, v2
	v_ashrrev_i32_e32 v3, 31, v2
	v_lshlrev_b64 v[2:3], 11, v[2:3]
	v_lshl_add_u64 v[2:3], v[4:5], 0, v[2:3]
	global_store_short v[2:3], v0, off
	v_cvt_f16_f32_e32 v0, v112
	v_cvt_f16_f32_e32 v4, v113
	v_cvt_f16_f32_e32 v5, v110
	v_cvt_f16_f32_e32 v36, v111
	global_store_short v[6:7], v0, off offset:64
	global_store_short v[8:9], v4, off offset:64
	global_store_short v[10:11], v5, off offset:64
	global_store_short v[12:13], v36, off offset:64
	v_cvt_f16_f32_e32 v0, v108
	v_cvt_f16_f32_e32 v4, v109
	v_cvt_f16_f32_e32 v5, v106
	v_cvt_f16_f32_e32 v6, v107
	global_store_short v[14:15], v0, off offset:64
	global_store_short v[16:17], v4, off offset:64
	global_store_short v[18:19], v5, off offset:64
	global_store_short v[20:21], v6, off offset:64
	v_cvt_f16_f32_e32 v0, v104
	v_cvt_f16_f32_e32 v4, v105
	v_cvt_f16_f32_e32 v5, v102
	v_cvt_f16_f32_e32 v6, v103
	global_store_short v[22:23], v0, off offset:64
	global_store_short v[24:25], v4, off offset:64
	global_store_short v[26:27], v5, off offset:64
	global_store_short v[28:29], v6, off offset:64
	v_cvt_f16_f32_e32 v0, v100
	v_cvt_f16_f32_e32 v4, v101
	v_cvt_f16_f32_e32 v5, v98
	v_cvt_f16_f32_e32 v6, v99
	global_store_short v[30:31], v0, off offset:64
	global_store_short v[32:33], v4, off offset:64
	global_store_short v[34:35], v5, off offset:64
	global_store_short v[2:3], v6, off offset:64
	s_branch .LBB0_1731
